# all 7 GEMM K-loops: next A tile via global_load_lds_dwordx4 issued right behind the weight-fragment loads (source-side swizzle), no register staging
# speedup vs baseline: 1.0826x; 1.0262x over previous
; #define MFMA16(a, b, c) __builtin_amdgcn_mfma_f32_16x16x32_bf16((a), (b), (c), 0, 0, 0)
; template <class Epi>
; DEVI void gemm_tile256b(const bf16_t* __restrict__ A, int lda, const bf16_t* __restrict__ Bt, int K,
;                         int m0, int n0, char* smem, Epi epi) {
;     ...
;   for (int kt = 0; kt < nk; ++kt) {
;     const char* base = smem + (kt & 1) * 32768;
;     const bool more = kt + 1 < nk;
;     if (more) {
; #pragma unroll
;       for (int i = 0; i < 8; ++i) ra[i] = *(const u32x4*)(ag + (size_t)(i * 32) * lda + (kt + 1) * 64);
;     }
; #pragma unroll
;     for (int i = 0; i < 4; ++i) b1[i] = *(const bf16x8*)(bp + ((size_t)i * kb32 + kt * 2 + 1) * 512);
;     {
;       bf16x8 af[8];
; #pragma unroll
;       for (int i = 0; i < 8; ++i) af[i] = *(const bf16x8*)(base + a_rd + i * 2048);
; #pragma unroll
;       for (int mi = 0; mi < 8; ++mi)
; #pragma unroll
;         for (int ni = 0; ni < 4; ++ni) acc[mi][ni] = MFMA16(b0[ni], af[mi], acc[mi][ni]);
;     }
;     if (more) {
; #pragma unroll
;       for (int i = 0; i < 4; ++i) b0[i] = *(const bf16x8*)(bp + ((size_t)i * kb32 + kt * 2 + 2) * 512);
;     }
;     {
;       bf16x8 af[8];
; #pragma unroll
;       for (int i = 0; i < 8; ++i) af[i] = *(const bf16x8*)(base + ((a_rd + i * 2048) ^ 64));
; #pragma unroll
;       for (int mi = 0; mi < 8; ++mi)
; #pragma unroll
;         for (int ni = 0; ni < 4; ++ni) acc[mi][ni] = MFMA16(b1[ni], af[mi], acc[mi][ni]);
;     }
;     if (more) {
;       char* nb = smem + ((kt + 1) & 1) * 32768 + lds_w;
; #pragma unroll
;       for (int i = 0; i < 8; ++i) *(u32x4*)(nb + i * 4096) = ra[i];
.LBB0_50:
	s_add_i32 s13, s1, 0xffff8000
	s_and_b32 s13, s13, 0x8000
	s_add_i32 s13, s13, 32
	v_add_u32_e32 v0, s13, v172
	ds_read_b128 v[146:149], v0
	ds_read_b128 v[150:153], v0 offset:2048
	v_lshl_add_u64 v[154:155], v[164:165], 0, s[28:29]
	v_add_co_u32_e32 v156, vcc, s34, v154
	s_waitcnt vmcnt(3) lgkmcnt(1)
	v_mfma_f32_16x16x32_bf16 v[122:125], v[10:13], v[146:149], v[122:125]
	v_addc_co_u32_e32 v157, vcc, 0, v155, vcc
	v_add_co_u32_e32 v158, vcc, s35, v154
	s_waitcnt vmcnt(2)
	v_mfma_f32_16x16x32_bf16 v[118:121], v[14:17], v[146:149], v[118:121]
	v_addc_co_u32_e32 v159, vcc, 0, v155, vcc
	v_add_co_u32_e32 v160, vcc, s38, v154
	s_waitcnt vmcnt(1)
	v_mfma_f32_16x16x32_bf16 v[114:117], v[6:9], v[146:149], v[114:117]
	v_addc_co_u32_e32 v161, vcc, 0, v155, vcc
	v_add_co_u32_e32 v182, vcc, s39, v154
	s_waitcnt vmcnt(0)
	v_mfma_f32_16x16x32_bf16 v[106:109], v[2:5], v[146:149], v[106:109]
	v_addc_co_u32_e32 v183, vcc, 0, v155, vcc
	v_lshl_add_u64 v[164:165], v[164:165], 0, s[64:65]
	s_waitcnt lgkmcnt(0)
	v_mfma_f32_16x16x32_bf16 v[102:105], v[10:13], v[150:153], v[102:105]
	v_mfma_f32_16x16x32_bf16 v[98:101], v[14:17], v[150:153], v[98:101]
	v_mfma_f32_16x16x32_bf16 v[82:85], v[6:9], v[150:153], v[82:85]
	v_mfma_f32_16x16x32_bf16 v[74:77], v[2:5], v[150:153], v[74:77]
	ds_read_b128 v[146:149], v0 offset:4096
	ds_read_b128 v[150:153], v0 offset:6144
	s_waitcnt lgkmcnt(1)
	v_mfma_f32_16x16x32_bf16 v[70:73], v[10:13], v[146:149], v[70:73]
	v_mfma_f32_16x16x32_bf16 v[66:69], v[14:17], v[146:149], v[66:69]
	v_mfma_f32_16x16x32_bf16 v[62:65], v[6:9], v[146:149], v[62:65]
	v_mfma_f32_16x16x32_bf16 v[54:57], v[2:5], v[146:149], v[54:57]
	s_waitcnt lgkmcnt(0)
	v_mfma_f32_16x16x32_bf16 v[42:45], v[10:13], v[150:153], v[42:45]
	v_mfma_f32_16x16x32_bf16 v[30:33], v[14:17], v[150:153], v[30:33]
	v_mfma_f32_16x16x32_bf16 v[34:37], v[6:9], v[150:153], v[34:37]
	v_mfma_f32_16x16x32_bf16 v[38:41], v[2:5], v[150:153], v[38:41]
	ds_read_b128 v[146:149], v0 offset:8192
	ds_read_b128 v[150:153], v0 offset:10240
	s_waitcnt lgkmcnt(1)
	v_mfma_f32_16x16x32_bf16 v[18:21], v[10:13], v[146:149], v[18:21]
	v_mfma_f32_16x16x32_bf16 v[26:29], v[14:17], v[146:149], v[26:29]
	v_mfma_f32_16x16x32_bf16 v[22:25], v[6:9], v[146:149], v[22:25]
	v_mfma_f32_16x16x32_bf16 v[50:53], v[2:5], v[146:149], v[50:53]
	s_waitcnt lgkmcnt(0)
	v_mfma_f32_16x16x32_bf16 v[58:61], v[10:13], v[150:153], v[58:61]
	v_mfma_f32_16x16x32_bf16 v[46:49], v[14:17], v[150:153], v[46:49]
	v_mfma_f32_16x16x32_bf16 v[94:97], v[6:9], v[150:153], v[94:97]
	v_mfma_f32_16x16x32_bf16 v[110:113], v[2:5], v[150:153], v[110:113]
	ds_read_b128 v[146:149], v0 offset:12288
	ds_read_b128 v[150:153], v0 offset:14336
	v_add_u32_e32 v0, s13, v171
	s_waitcnt lgkmcnt(1)
	v_mfma_f32_16x16x32_bf16 v[78:81], v[10:13], v[146:149], v[78:81]
	v_mfma_f32_16x16x32_bf16 v[90:93], v[14:17], v[146:149], v[90:93]
	v_mfma_f32_16x16x32_bf16 v[86:89], v[6:9], v[146:149], v[86:89]
	v_mfma_f32_16x16x32_bf16 v[142:145], v[2:5], v[146:149], v[142:145]
	global_load_dwordx4 v[146:149], v[156:157], off offset:1024
	ds_read_b128 v[174:177], v0
	ds_read_b128 v[178:181], v0 offset:2048
	s_waitcnt lgkmcnt(2)
	v_mfma_f32_16x16x32_bf16 v[138:141], v[10:13], v[150:153], v[138:141]
	global_load_dwordx4 v[10:13], v[156:157], off offset:2048
	v_mfma_f32_16x16x32_bf16 v[134:137], v[14:17], v[150:153], v[134:137]
	v_mfma_f32_16x16x32_bf16 v[130:133], v[6:9], v[150:153], v[130:133]
	v_mfma_f32_16x16x32_bf16 v[126:129], v[2:5], v[150:153], v[126:129]
	global_load_dwordx4 v[150:153], v[158:159], off offset:1024
	global_load_dwordx4 v[14:17], v[158:159], off offset:2048
	global_load_dwordx4 v[154:157], v[160:161], off offset:1024
	global_load_dwordx4 v[6:9], v[160:161], off offset:2048
	s_nop 0
	global_load_dwordx4 v[158:161], v[182:183], off offset:1024
	global_load_dwordx4 v[2:5], v[182:183], off offset:2048
	v_lshrrev_b32_e32 v195, 6, v206
	v_lshl_add_u64 v[190:191], v[166:167], 0, s[28:29]
	v_lshrrev_b32_e32 v194, 3, v206
	v_readfirstlane_b32 s99, v195
	v_and_b32_e32 v194, 7, v194
	s_and_b32 s98, s1, 0x8000
	v_lshlrev_b32_e32 v194, 4, v194
	s_lshl_b32 s99, s99, 10
	v_xor_b32_e32 v190, v194, v190
	s_add_u32 s98, s98, s99
	s_add_u32 s98, s98, 32
	s_mov_b32 s101, 0
	s_add_u32 s100, s18, 0x80
	v_lshl_add_u64 v[192:193], v[190:191], 0, s[100:101]
	s_mov_b32 m0, s98
	s_nop 0
	global_load_lds_dwordx4 v[192:193], off
	s_mov_b32 s100, 0x9c63080
	v_lshl_add_u64 v[192:193], v[190:191], 0, s[100:101]
	s_add_u32 m0, s98, 0x1000
	s_nop 0
	global_load_lds_dwordx4 v[192:193], off
	s_mov_b32 s100, 0x9c73080
	v_lshl_add_u64 v[192:193], v[190:191], 0, s[100:101]
	s_add_u32 m0, s98, 0x2000
	s_nop 0
	global_load_lds_dwordx4 v[192:193], off
	s_add_u32 s100, s24, 0x80
	v_lshl_add_u64 v[192:193], v[190:191], 0, s[100:101]
	s_add_u32 m0, s98, 0x3000
	s_nop 0
	global_load_lds_dwordx4 v[192:193], off
	s_mov_b32 s100, 0x9c93080
	v_lshl_add_u64 v[192:193], v[190:191], 0, s[100:101]
	s_add_u32 m0, s98, 0x4000
	s_nop 0
	global_load_lds_dwordx4 v[192:193], off
	s_mov_b32 s100, 0x9ca3080
	v_lshl_add_u64 v[192:193], v[190:191], 0, s[100:101]
	s_add_u32 m0, s98, 0x5000
	s_nop 0
	global_load_lds_dwordx4 v[192:193], off
	s_add_u32 s100, s25, 0x80
	v_lshl_add_u64 v[192:193], v[190:191], 0, s[100:101]
	s_add_u32 m0, s98, 0x6000
	s_nop 0
	global_load_lds_dwordx4 v[192:193], off
	s_mov_b32 s100, 0x9cc3080
	v_lshl_add_u64 v[192:193], v[190:191], 0, s[100:101]
	s_add_u32 m0, s98, 0x7000
	s_nop 0
	global_load_lds_dwordx4 v[192:193], off
	s_waitcnt vmcnt(15) lgkmcnt(1)
	v_mfma_f32_16x16x32_bf16 v[122:125], v[146:149], v[174:177], v[122:125]
	s_nop 0
	s_waitcnt vmcnt(13)
; #define MFMA16(a, b, c) __builtin_amdgcn_mfma_f32_16x16x32_bf16((a), (b), (c), 0, 0, 0)
; template <class Epi>
; DEVI void gemm_tile256b(const bf16_t* __restrict__ A, int lda, const bf16_t* __restrict__ Bt, int K,
;                         int m0, int n0, char* smem, Epi epi) {
;     ...
;     if (more) {
; #pragma unroll
;       for (int i = 0; i < 4; ++i) b0[i] = *(const bf16x8*)(bp + ((size_t)i * kb32 + kt * 2 + 2) * 512);
;     }
;     {
;       bf16x8 af[8];
; #pragma unroll
;       for (int i = 0; i < 8; ++i) af[i] = *(const bf16x8*)(base + ((a_rd + i * 2048) ^ 64));
; #pragma unroll
;       for (int mi = 0; mi < 8; ++mi)
; #pragma unroll
;         for (int ni = 0; ni < 4; ++ni) acc[mi][ni] = MFMA16(b1[ni], af[mi], acc[mi][ni]);
;     }
;     if (more) {
;       char* nb = smem + ((kt + 1) & 1) * 32768 + lds_w;
; #pragma unroll
;       for (int i = 0; i < 8; ++i) *(u32x4*)(nb + i * 4096) = ra[i];
;     }
;     __syncthreads();
	v_mfma_f32_16x16x32_bf16 v[118:121], v[150:153], v[174:177], v[118:121]
	s_waitcnt vmcnt(11)
	v_mfma_f32_16x16x32_bf16 v[114:117], v[154:157], v[174:177], v[114:117]
	s_waitcnt vmcnt(9)
	v_mfma_f32_16x16x32_bf16 v[106:109], v[158:161], v[174:177], v[106:109]
	s_waitcnt lgkmcnt(0)
	v_mfma_f32_16x16x32_bf16 v[102:105], v[146:149], v[178:181], v[102:105]
	v_mfma_f32_16x16x32_bf16 v[98:101], v[150:153], v[178:181], v[98:101]
	s_nop 0
	v_mfma_f32_16x16x32_bf16 v[82:85], v[154:157], v[178:181], v[82:85]
	s_nop 0
	v_mfma_f32_16x16x32_bf16 v[74:77], v[158:161], v[178:181], v[74:77]
	ds_read_b128 v[174:177], v0 offset:4096
	ds_read_b128 v[178:181], v0 offset:6144
	s_waitcnt lgkmcnt(1)
	v_mfma_f32_16x16x32_bf16 v[70:73], v[146:149], v[174:177], v[70:73]
	s_and_b32 s13, s1, 0x8000
	v_mfma_f32_16x16x32_bf16 v[66:69], v[150:153], v[174:177], v[66:69]
	s_add_i32 s1, s1, 0x8000
	v_lshl_add_u64 v[166:167], v[166:167], 0, s[60:61]
	s_cmp_eq_u32 s1, 0x80000
	v_mfma_f32_16x16x32_bf16 v[62:65], v[154:157], v[174:177], v[62:65]
	v_mfma_f32_16x16x32_bf16 v[54:57], v[158:161], v[174:177], v[54:57]
	s_waitcnt lgkmcnt(0)
	v_mfma_f32_16x16x32_bf16 v[42:45], v[146:149], v[178:181], v[42:45]
	v_mfma_f32_16x16x32_bf16 v[30:33], v[150:153], v[178:181], v[30:33]
	v_mfma_f32_16x16x32_bf16 v[34:37], v[154:157], v[178:181], v[34:37]
	v_mfma_f32_16x16x32_bf16 v[38:41], v[158:161], v[178:181], v[38:41]
	ds_read_b128 v[174:177], v0 offset:8192
	ds_read_b128 v[178:181], v0 offset:10240
	s_waitcnt lgkmcnt(1)
	v_mfma_f32_16x16x32_bf16 v[18:21], v[146:149], v[174:177], v[18:21]
	v_mfma_f32_16x16x32_bf16 v[26:29], v[150:153], v[174:177], v[26:29]
	v_mfma_f32_16x16x32_bf16 v[22:25], v[154:157], v[174:177], v[22:25]
	v_mfma_f32_16x16x32_bf16 v[50:53], v[158:161], v[174:177], v[50:53]
	s_waitcnt lgkmcnt(0)
	v_mfma_f32_16x16x32_bf16 v[58:61], v[146:149], v[178:181], v[58:61]
	v_mfma_f32_16x16x32_bf16 v[46:49], v[150:153], v[178:181], v[46:49]
	v_mfma_f32_16x16x32_bf16 v[94:97], v[154:157], v[178:181], v[94:97]
	v_mfma_f32_16x16x32_bf16 v[110:113], v[158:161], v[178:181], v[110:113]
	ds_read_b128 v[178:181], v0 offset:12288
	ds_read_b128 v[182:185], v0 offset:14336
	s_nop 0
	s_nop 0
	s_nop 0
	s_nop 0
	s_nop 0
	s_waitcnt lgkmcnt(1)
	v_mfma_f32_16x16x32_bf16 v[78:81], v[146:149], v[178:181], v[78:81]
	v_mfma_f32_16x16x32_bf16 v[90:93], v[150:153], v[178:181], v[90:93]
	v_mfma_f32_16x16x32_bf16 v[86:89], v[154:157], v[178:181], v[86:89]
	s_waitcnt vmcnt(0) lgkmcnt(0)
	s_barrier
	v_mfma_f32_16x16x32_bf16 v[142:145], v[158:161], v[178:181], v[142:145]
	v_mfma_f32_16x16x32_bf16 v[138:141], v[146:149], v[182:185], v[138:141]
	v_mfma_f32_16x16x32_bf16 v[134:137], v[150:153], v[182:185], v[134:137]
	v_mfma_f32_16x16x32_bf16 v[130:133], v[154:157], v[182:185], v[130:133]
	v_mfma_f32_16x16x32_bf16 v[126:129], v[158:161], v[182:185], v[126:129]
	s_cmp_eq_u32 s1, 0x80000
	s_cbranch_scc0 .LBB0_50
	v_add_u32_e32 v0, 32, v172
	ds_read_b128 v[146:149], v0 offset:32768
	ds_read_b128 v[150:153], v0 offset:34816
	s_waitcnt lgkmcnt(1)
	v_mfma_f32_16x16x32_bf16 v[122:125], v[10:13], v[146:149], v[122:125]
	v_mfma_f32_16x16x32_bf16 v[118:121], v[14:17], v[146:149], v[118:121]
	v_mfma_f32_16x16x32_bf16 v[114:117], v[6:9], v[146:149], v[114:117]
	v_mfma_f32_16x16x32_bf16 v[106:109], v[2:5], v[146:149], v[106:109]
	s_waitcnt lgkmcnt(0)
	v_mfma_f32_16x16x32_bf16 v[102:105], v[10:13], v[150:153], v[102:105]
	v_mfma_f32_16x16x32_bf16 v[98:101], v[14:17], v[150:153], v[98:101]
	v_mfma_f32_16x16x32_bf16 v[82:85], v[6:9], v[150:153], v[82:85]
	v_mfma_f32_16x16x32_bf16 v[74:77], v[2:5], v[150:153], v[74:77]
	ds_read_b128 v[146:149], v0 offset:36864
	ds_read_b128 v[150:153], v0 offset:38912
	s_waitcnt lgkmcnt(1)
	v_mfma_f32_16x16x32_bf16 v[70:73], v[10:13], v[146:149], v[70:73]
	v_mfma_f32_16x16x32_bf16 v[66:69], v[14:17], v[146:149], v[66:69]
	v_mfma_f32_16x16x32_bf16 v[62:65], v[6:9], v[146:149], v[62:65]
	v_mfma_f32_16x16x32_bf16 v[54:57], v[2:5], v[146:149], v[54:57]
	s_waitcnt lgkmcnt(0)
	v_mfma_f32_16x16x32_bf16 v[42:45], v[10:13], v[150:153], v[42:45]
	v_mfma_f32_16x16x32_bf16 v[30:33], v[14:17], v[150:153], v[30:33]
	v_mfma_f32_16x16x32_bf16 v[34:37], v[6:9], v[150:153], v[34:37]
	v_mfma_f32_16x16x32_bf16 v[38:41], v[2:5], v[150:153], v[38:41]
	ds_read_b128 v[146:149], v0 offset:40960
	ds_read_b128 v[150:153], v0 offset:43008
	s_waitcnt lgkmcnt(1)
	v_mfma_f32_16x16x32_bf16 v[18:21], v[10:13], v[146:149], v[18:21]
	v_mfma_f32_16x16x32_bf16 v[26:29], v[14:17], v[146:149], v[26:29]
	v_mfma_f32_16x16x32_bf16 v[22:25], v[6:9], v[146:149], v[22:25]
	v_mfma_f32_16x16x32_bf16 v[50:53], v[2:5], v[146:149], v[50:53]
	s_waitcnt lgkmcnt(0)
	v_mfma_f32_16x16x32_bf16 v[146:149], v[10:13], v[150:153], v[58:61]
	v_mfma_f32_16x16x32_bf16 v[154:157], v[14:17], v[150:153], v[46:49]
	s_nop 2
	ds_read_b128 v[46:49], v0 offset:45056
	ds_read_b128 v[58:61], v0 offset:47104
	v_add_u32_e32 v0, 32, v171
	s_waitcnt lgkmcnt(1)
	v_mfma_f32_16x16x32_bf16 v[164:167], v[10:13], v[46:49], v[78:81]
	s_nop 2
	v_add_co_u32_e32 v78, vcc, 0x7000, v162
	v_mfma_f32_16x16x32_bf16 v[172:175], v[14:17], v[46:49], v[90:93]
	s_nop 0
	v_addc_co_u32_e32 v79, vcc, 0, v163, vcc
	v_mfma_f32_16x16x32_bf16 v[176:179], v[6:9], v[46:49], v[86:89]
	v_mfma_f32_16x16x32_bf16 v[142:145], v[2:5], v[46:49], v[142:145]
	v_add_co_u32_e32 v46, vcc, 0xf000, v162
	s_nop 1
	v_addc_co_u32_e32 v47, vcc, 0, v163, vcc
	s_waitcnt lgkmcnt(0)
; #define MFMA16(a, b, c) __builtin_amdgcn_mfma_f32_16x16x32_bf16((a), (b), (c), 0, 0, 0)
; template <class Epi>
; DEVI void gemm_tile256b(const bf16_t* __restrict__ A, int lda, const bf16_t* __restrict__ Bt, int K,
;                         int m0, int n0, char* smem, Epi epi) {
;     ...
;     {
;       bf16x8 af[8];
; #pragma unroll
;       for (int i = 0; i < 8; ++i) af[i] = *(const bf16x8*)(base + ((a_rd + i * 2048) ^ 64));
; #pragma unroll
;       for (int mi = 0; mi < 8; ++mi)
; #pragma unroll
;         for (int ni = 0; ni < 4; ++ni) acc[mi][ni] = MFMA16(b1[ni], af[mi], acc[mi][ni]);
;     }
;     if (more) {
;       char* nb = smem + ((kt + 1) & 1) * 32768 + lds_w;
; #pragma unroll
;       for (int i = 0; i < 8; ++i) *(u32x4*)(nb + i * 4096) = ra[i];
;     }
;     __syncthreads();
;   }
; #pragma unroll
;   for (int mi = 0; mi < 8; ++mi)
; #pragma unroll
;     for (int ni = 0; ni < 4; ++ni)
;       epi(m0 + wm * 128 + mi * 16 + l15, n0 + wn * 64 + ni * 16 + quad * 4, acc[mi][ni]);
;   DEVI void operator()(int m, int n, f32x4 v) const {
;     if (m >= L) return;
;     float* h = hfrow(p, m) + n;
;     const float* src = (first && m >= 16) ? p.in[0] + (size_t)(m - 16) * 1024 + n : h;
;     f32x4 o = *(const f32x4*)src;
;     o = o * ALPHA + v;
;     *(f32x4*)h = o;
;   }
	v_mfma_f32_16x16x32_bf16 v[10:13], v[10:13], v[58:61], v[138:141]
	global_load_dwordx4 v[180:183], v[46:47], off offset:3072
	s_nop 1
	global_load_dwordx4 v[138:141], v[78:79], off offset:3072
	v_add_co_u32_e32 v78, vcc, 0x17000, v162
	v_mfma_f32_16x16x32_bf16 v[158:161], v[6:9], v[150:153], v[94:97]
	s_nop 0
	v_addc_co_u32_e32 v79, vcc, 0, v163, vcc
	v_mfma_f32_16x16x32_bf16 v[150:153], v[2:5], v[150:153], v[110:113]
	v_mfma_f32_16x16x32_bf16 v[134:137], v[14:17], v[58:61], v[134:137]
	ds_read_b128 v[14:17], v0 offset:32768
	v_mfma_f32_16x16x32_bf16 v[6:9], v[6:9], v[58:61], v[130:133]
	v_mfma_f32_16x16x32_bf16 v[2:5], v[2:5], v[58:61], v[126:129]
	v_add_co_u32_e32 v58, vcc, 0x1f000, v162
	s_nop 0
	global_load_dwordx4 v[130:133], v[78:79], off offset:3072
	v_addc_co_u32_e32 v59, vcc, 0, v163, vcc
	global_load_dwordx4 v[190:193], v[58:59], off offset:3072
	ds_read_b128 v[46:49], v0 offset:34816
	s_waitcnt vmcnt(2) lgkmcnt(1)
	v_mfma_f32_16x16x32_bf16 v[126:129], v[138:141], v[14:17], v[122:125]
	v_mfma_f32_16x16x32_bf16 v[122:125], v[180:183], v[14:17], v[118:121]
	s_waitcnt vmcnt(1)
	v_mfma_f32_16x16x32_bf16 v[118:121], v[130:133], v[14:17], v[114:117]
	s_waitcnt vmcnt(0)
	v_mfma_f32_16x16x32_bf16 v[114:117], v[190:193], v[14:17], v[106:109]
	s_waitcnt lgkmcnt(0)
	v_mfma_f32_16x16x32_bf16 v[110:113], v[138:141], v[46:49], v[102:105]
	v_mfma_f32_16x16x32_bf16 v[106:109], v[180:183], v[46:49], v[98:101]
	v_mfma_f32_16x16x32_bf16 v[102:105], v[130:133], v[46:49], v[82:85]
	v_mfma_f32_16x16x32_bf16 v[98:101], v[190:193], v[46:49], v[74:77]
	ds_read_b128 v[14:17], v0 offset:36864
	ds_read_b128 v[46:49], v0 offset:38912
	s_waitcnt lgkmcnt(1)
	v_mfma_f32_16x16x32_bf16 v[94:97], v[138:141], v[14:17], v[70:73]
	v_mfma_f32_16x16x32_bf16 v[90:93], v[180:183], v[14:17], v[66:69]
	v_mfma_f32_16x16x32_bf16 v[86:89], v[130:133], v[14:17], v[62:65]
	v_mfma_f32_16x16x32_bf16 v[82:85], v[190:193], v[14:17], v[54:57]
	s_waitcnt lgkmcnt(0)
	v_mfma_f32_16x16x32_bf16 v[74:77], v[180:183], v[46:49], v[30:33]
	ds_read_b128 v[14:17], v0 offset:40960
	s_nop 1
	ds_read_b128 v[30:33], v0 offset:43008
	v_mfma_f32_16x16x32_bf16 v[78:81], v[138:141], v[46:49], v[42:45]
	v_mfma_f32_16x16x32_bf16 v[70:73], v[130:133], v[46:49], v[34:37]
	v_mfma_f32_16x16x32_bf16 v[66:69], v[190:193], v[46:49], v[38:41]
	s_waitcnt lgkmcnt(1)
	v_mfma_f32_16x16x32_bf16 v[62:65], v[138:141], v[14:17], v[18:21]
	v_mfma_f32_16x16x32_bf16 v[58:61], v[180:183], v[14:17], v[26:29]
	v_mfma_f32_16x16x32_bf16 v[54:57], v[130:133], v[14:17], v[22:25]
	v_mfma_f32_16x16x32_bf16 v[50:53], v[190:193], v[14:17], v[50:53]
	s_waitcnt lgkmcnt(0)
	v_mfma_f32_16x16x32_bf16 v[46:49], v[138:141], v[30:33], v[146:149]
	ds_read_b128 v[14:17], v0 offset:45056
	s_nop 1
	ds_read_b128 v[146:149], v0 offset:47104
	v_and_b32_e32 v0, 0xffffff80, v168
	s_waitcnt lgkmcnt(0)
	v_mfma_f32_16x16x32_bf16 v[42:45], v[180:183], v[30:33], v[154:157]
	s_barrier
	v_mfma_f32_16x16x32_bf16 v[38:41], v[130:133], v[30:33], v[158:161]
	v_mfma_f32_16x16x32_bf16 v[34:37], v[190:193], v[30:33], v[150:153]
	v_mfma_f32_16x16x32_bf16 v[30:33], v[138:141], v[14:17], v[164:167]
	v_mfma_f32_16x16x32_bf16 v[26:29], v[180:183], v[14:17], v[172:175]
	v_mfma_f32_16x16x32_bf16 v[22:25], v[130:133], v[14:17], v[176:179]
	v_mfma_f32_16x16x32_bf16 v[18:21], v[190:193], v[14:17], v[142:145]
	v_mfma_f32_16x16x32_bf16 v[14:17], v[138:141], v[146:149], v[10:13]
	v_mfma_f32_16x16x32_bf16 v[10:13], v[180:183], v[146:149], v[134:137]
	v_mfma_f32_16x16x32_bf16 v[6:9], v[130:133], v[146:149], v[6:9]
	s_nop 1
	v_add_u32_e32 v134, s0, v0
	v_and_or_b32 v132, v168, 15, v134
	v_lshl_or_b32 v130, v169, 2, v170
	v_mfma_f32_16x16x32_bf16 v[2:5], v[190:193], v[146:149], v[2:5]
	s_movk_i32 s0, 0x4010
	v_cmp_gt_i32_e32 vcc, s0, v132
	v_ashrrev_i32_e32 v131, 31, v130
	s_and_saveexec_b64 s[38:39], vcc
	s_cbranch_execz .LBB0_53
	v_lshlrev_b32_e32 v136, 10, v132
	v_add_u32_e32 v0, -16, v132
	v_ashrrev_i32_e32 v137, 31, v136
	v_lshlrev_b64 v[138:139], 12, v[0:1]
	v_lshl_add_u64 v[136:137], v[136:137], 2, s[16:17]
	v_lshl_add_u64 v[140:141], s[26:27], 0, v[138:139]
	v_cmp_gt_i32_e64 s[0:1], 16, v132
	v_readlane_b32 s68, v248, 63
	v_readlane_b32 s69, v247, 0
	v_cndmask_b32_e64 v137, v141, v137, s[0:1]
	v_cndmask_b32_e64 v136, v140, v136, s[0:1]
	v_lshlrev_b64 v[140:141], 2, v[130:131]
	v_cmp_lt_i32_e32 vcc, 15, v132
	v_lshl_add_u64 v[142:143], v[136:137], 0, v[140:141]
	v_lshl_add_u64 v[136:137], s[68:69], 0, v[138:139]
	v_lshl_add_u64 v[136:137], v[136:137], 0, v[140:141]
	s_and_b64 vcc, s[36:37], vcc
	v_cndmask_b32_e32 v141, v143, v137, vcc
	v_cndmask_b32_e32 v140, v142, v136, vcc
	global_load_dwordx4 v[136:139], v[140:141], off
	v_readlane_b32 s70, v247, 1
	v_readlane_b32 s71, v247, 2
	v_readlane_b32 s72, v247, 3
	v_readlane_b32 s73, v247, 4
	v_readlane_b32 s74, v247, 5
	v_readlane_b32 s75, v247, 6
	v_readlane_b32 s76, v247, 7
	v_readlane_b32 s77, v247, 8
	v_readlane_b32 s78, v247, 9
	v_readlane_b32 s79, v247, 10
	v_readlane_b32 s80, v247, 11
	v_readlane_b32 s81, v247, 12
	v_readlane_b32 s82, v247, 13
	v_readlane_b32 s83, v247, 14
	s_waitcnt vmcnt(0)
	v_pk_fma_f32 v[128:129], v[138:139], s[66:67], v[128:129] op_sel_hi:[1,0,1]
	v_pk_fma_f32 v[126:127], v[136:137], s[66:67], v[126:127] op_sel_hi:[1,0,1]
	global_store_dwordx4 v[142:143], v[126:129], off
	global_load_dwordx4 v[126:129], v[140:141], off offset:64
	s_waitcnt vmcnt(0)
	v_pk_fma_f32 v[124:125], v[128:129], s[66:67], v[124:125] op_sel_hi:[1,0,1]
	v_pk_fma_f32 v[122:123], v[126:127], s[66:67], v[122:123] op_sel_hi:[1,0,1]
	global_store_dwordx4 v[142:143], v[122:125], off offset:64
	global_load_dwordx4 v[122:125], v[140:141], off offset:128
	s_waitcnt vmcnt(0)
	v_pk_fma_f32 v[120:121], v[124:125], s[66:67], v[120:121] op_sel_hi:[1,0,1]
	v_pk_fma_f32 v[118:119], v[122:123], s[66:67], v[118:119] op_sel_hi:[1,0,1]
	global_store_dwordx4 v[142:143], v[118:121], off offset:128
	global_load_dwordx4 v[118:121], v[140:141], off offset:192
	s_waitcnt vmcnt(0)
	v_pk_fma_f32 v[116:117], v[120:121], s[66:67], v[116:117] op_sel_hi:[1,0,1]
	v_pk_fma_f32 v[114:115], v[118:119], s[66:67], v[114:115] op_sel_hi:[1,0,1]
	global_store_dwordx4 v[142:143], v[114:117], off offset:192

; #define MFMA16(a, b, c) __builtin_amdgcn_mfma_f32_16x16x32_bf16((a), (b), (c), 0, 0, 0)
; template <class Epi>
; DEVI void gemm_tile256b(const bf16_t* __restrict__ A, int lda, const bf16_t* __restrict__ Bt, int K,
;                         int m0, int n0, char* smem, Epi epi) {
;     ...
;   for (int kt = 0; kt < nk; ++kt) {
;     const char* base = smem + (kt & 1) * 32768;
;     const bool more = kt + 1 < nk;
;     if (more) {
; #pragma unroll
;       for (int i = 0; i < 8; ++i) ra[i] = *(const u32x4*)(ag + (size_t)(i * 32) * lda + (kt + 1) * 64);
;     }
; #pragma unroll
;     for (int i = 0; i < 4; ++i) b1[i] = *(const bf16x8*)(bp + ((size_t)i * kb32 + kt * 2 + 1) * 512);
;     {
;       bf16x8 af[8];
; #pragma unroll
;       for (int i = 0; i < 8; ++i) af[i] = *(const bf16x8*)(base + a_rd + i * 2048);
; #pragma unroll
;       for (int mi = 0; mi < 8; ++mi)
; #pragma unroll
;         for (int ni = 0; ni < 4; ++ni) acc[mi][ni] = MFMA16(b0[ni], af[mi], acc[mi][ni]);
;     }
;     if (more) {
; #pragma unroll
;       for (int i = 0; i < 4; ++i) b0[i] = *(const bf16x8*)(bp + ((size_t)i * kb32 + kt * 2 + 2) * 512);
;     }
;     {
;       bf16x8 af[8];
; #pragma unroll
;       for (int i = 0; i < 8; ++i) af[i] = *(const bf16x8*)(base + ((a_rd + i * 2048) ^ 64));
; #pragma unroll
;       for (int mi = 0; mi < 8; ++mi)
; #pragma unroll
;         for (int ni = 0; ni < 4; ++ni) acc[mi][ni] = MFMA16(b1[ni], af[mi], acc[mi][ni]);
;     }
;     if (more) {
;       char* nb = smem + ((kt + 1) & 1) * 32768 + lds_w;
; #pragma unroll
;       for (int i = 0; i < 8; ++i) *(u32x4*)(nb + i * 4096) = ra[i];
.LBB0_324:
	s_add_i32 s13, s1, 0xffff8000
	s_and_b32 s13, s13, 0x8000
	s_add_i32 s13, s13, 32
	v_add_u32_e32 v0, s13, v172
	ds_read_b128 v[146:149], v0
	ds_read_b128 v[150:153], v0 offset:2048
	v_lshl_add_u64 v[154:155], v[164:165], 0, s[28:29]
	v_add_co_u32_e32 v156, vcc, s24, v154
	s_waitcnt vmcnt(3) lgkmcnt(1)
	v_mfma_f32_16x16x32_bf16 v[122:125], v[10:13], v[146:149], v[122:125]
	v_addc_co_u32_e32 v157, vcc, 0, v155, vcc
	v_add_co_u32_e32 v158, vcc, s25, v154
	s_waitcnt vmcnt(2)
	v_mfma_f32_16x16x32_bf16 v[118:121], v[14:17], v[146:149], v[118:121]
	v_addc_co_u32_e32 v159, vcc, 0, v155, vcc
	v_add_co_u32_e32 v160, vcc, s34, v154
	s_waitcnt vmcnt(1)
	v_mfma_f32_16x16x32_bf16 v[114:117], v[6:9], v[146:149], v[114:117]
	v_addc_co_u32_e32 v161, vcc, 0, v155, vcc
	v_add_co_u32_e32 v182, vcc, s35, v154
	s_waitcnt vmcnt(0)
	v_mfma_f32_16x16x32_bf16 v[106:109], v[2:5], v[146:149], v[106:109]
	v_addc_co_u32_e32 v183, vcc, 0, v155, vcc
	v_lshl_add_u64 v[164:165], v[164:165], 0, s[64:65]
	s_waitcnt lgkmcnt(0)
	v_mfma_f32_16x16x32_bf16 v[102:105], v[10:13], v[150:153], v[102:105]
	v_mfma_f32_16x16x32_bf16 v[98:101], v[14:17], v[150:153], v[98:101]
	v_mfma_f32_16x16x32_bf16 v[82:85], v[6:9], v[150:153], v[82:85]
	v_mfma_f32_16x16x32_bf16 v[74:77], v[2:5], v[150:153], v[74:77]
	ds_read_b128 v[146:149], v0 offset:4096
	ds_read_b128 v[150:153], v0 offset:6144
	s_waitcnt lgkmcnt(1)
	v_mfma_f32_16x16x32_bf16 v[70:73], v[10:13], v[146:149], v[70:73]
	v_mfma_f32_16x16x32_bf16 v[66:69], v[14:17], v[146:149], v[66:69]
	v_mfma_f32_16x16x32_bf16 v[62:65], v[6:9], v[146:149], v[62:65]
	v_mfma_f32_16x16x32_bf16 v[54:57], v[2:5], v[146:149], v[54:57]
	s_waitcnt lgkmcnt(0)
	v_mfma_f32_16x16x32_bf16 v[42:45], v[10:13], v[150:153], v[42:45]
	v_mfma_f32_16x16x32_bf16 v[30:33], v[14:17], v[150:153], v[30:33]
	v_mfma_f32_16x16x32_bf16 v[38:41], v[6:9], v[150:153], v[38:41]
	v_mfma_f32_16x16x32_bf16 v[26:29], v[2:5], v[150:153], v[26:29]
	ds_read_b128 v[146:149], v0 offset:8192
	ds_read_b128 v[150:153], v0 offset:10240
	s_waitcnt lgkmcnt(1)
	v_mfma_f32_16x16x32_bf16 v[22:25], v[10:13], v[146:149], v[22:25]
	v_mfma_f32_16x16x32_bf16 v[18:21], v[14:17], v[146:149], v[18:21]
	v_mfma_f32_16x16x32_bf16 v[34:37], v[6:9], v[146:149], v[34:37]
	v_mfma_f32_16x16x32_bf16 v[46:49], v[2:5], v[146:149], v[46:49]
	s_waitcnt lgkmcnt(0)
	v_mfma_f32_16x16x32_bf16 v[50:53], v[10:13], v[150:153], v[50:53]
	v_mfma_f32_16x16x32_bf16 v[58:61], v[14:17], v[150:153], v[58:61]
	v_mfma_f32_16x16x32_bf16 v[94:97], v[6:9], v[150:153], v[94:97]
	v_mfma_f32_16x16x32_bf16 v[110:113], v[2:5], v[150:153], v[110:113]
	ds_read_b128 v[146:149], v0 offset:12288
	ds_read_b128 v[150:153], v0 offset:14336
	v_add_u32_e32 v0, s13, v171
	s_waitcnt lgkmcnt(1)
	v_mfma_f32_16x16x32_bf16 v[78:81], v[10:13], v[146:149], v[78:81]
	v_mfma_f32_16x16x32_bf16 v[90:93], v[14:17], v[146:149], v[90:93]
	v_mfma_f32_16x16x32_bf16 v[86:89], v[6:9], v[146:149], v[86:89]
	v_mfma_f32_16x16x32_bf16 v[142:145], v[2:5], v[146:149], v[142:145]
	global_load_dwordx4 v[146:149], v[156:157], off offset:1024
	ds_read_b128 v[174:177], v0
	ds_read_b128 v[178:181], v0 offset:2048
	s_waitcnt lgkmcnt(2)
	v_mfma_f32_16x16x32_bf16 v[138:141], v[10:13], v[150:153], v[138:141]
	global_load_dwordx4 v[10:13], v[156:157], off offset:2048
	v_mfma_f32_16x16x32_bf16 v[134:137], v[14:17], v[150:153], v[134:137]
	v_mfma_f32_16x16x32_bf16 v[130:133], v[6:9], v[150:153], v[130:133]
	v_mfma_f32_16x16x32_bf16 v[126:129], v[2:5], v[150:153], v[126:129]
	global_load_dwordx4 v[150:153], v[158:159], off offset:1024
	global_load_dwordx4 v[14:17], v[158:159], off offset:2048
	global_load_dwordx4 v[154:157], v[160:161], off offset:1024
	global_load_dwordx4 v[6:9], v[160:161], off offset:2048
	s_nop 0
	global_load_dwordx4 v[158:161], v[182:183], off offset:1024
	global_load_dwordx4 v[2:5], v[182:183], off offset:2048
	v_lshrrev_b32_e32 v195, 6, v206
	v_lshl_add_u64 v[190:191], v[166:167], 0, s[28:29]
	v_lshrrev_b32_e32 v194, 3, v206
	v_readfirstlane_b32 s99, v195
	v_and_b32_e32 v194, 7, v194
	s_and_b32 s98, s1, 0x8000
	v_lshlrev_b32_e32 v194, 4, v194
	s_lshl_b32 s99, s99, 10
	v_xor_b32_e32 v190, v194, v190
	s_add_u32 s98, s98, s99
	s_add_u32 s98, s98, 32
	s_mov_b32 s101, 0
	s_add_u32 s100, s16, 0x80
	v_lshl_add_u64 v[192:193], v[190:191], 0, s[100:101]
	s_mov_b32 m0, s98
	s_nop 0
	global_load_lds_dwordx4 v[192:193], off
	s_add_u32 s100, s17, 0x80
	v_lshl_add_u64 v[192:193], v[190:191], 0, s[100:101]
	s_add_u32 m0, s98, 0x1000
	s_nop 0
	global_load_lds_dwordx4 v[192:193], off
	s_add_u32 s100, s18, 0x80
	v_lshl_add_u64 v[192:193], v[190:191], 0, s[100:101]
	s_add_u32 m0, s98, 0x2000
	s_nop 0
	global_load_lds_dwordx4 v[192:193], off
	s_mov_b32 s100, 0x9ce3080
	v_lshl_add_u64 v[192:193], v[190:191], 0, s[100:101]
	s_add_u32 m0, s98, 0x3000
	s_nop 0
	global_load_lds_dwordx4 v[192:193], off
	s_mov_b32 s100, 0x9d13080
	v_lshl_add_u64 v[192:193], v[190:191], 0, s[100:101]
	s_add_u32 m0, s98, 0x4000
	s_nop 0
	global_load_lds_dwordx4 v[192:193], off
	s_mov_b32 s100, 0x9d43080
	v_lshl_add_u64 v[192:193], v[190:191], 0, s[100:101]
	s_add_u32 m0, s98, 0x5000
	s_nop 0
	global_load_lds_dwordx4 v[192:193], off
	s_mov_b32 s100, 0x9d73080
	v_lshl_add_u64 v[192:193], v[190:191], 0, s[100:101]
	s_add_u32 m0, s98, 0x6000
	s_nop 0
	global_load_lds_dwordx4 v[192:193], off
	s_mov_b32 s100, 0x9da3080
	v_lshl_add_u64 v[192:193], v[190:191], 0, s[100:101]
	s_add_u32 m0, s98, 0x7000
	s_nop 0
	global_load_lds_dwordx4 v[192:193], off
	s_waitcnt vmcnt(15) lgkmcnt(1)
	v_mfma_f32_16x16x32_bf16 v[122:125], v[146:149], v[174:177], v[122:125]
	s_waitcnt vmcnt(13)
; #define MFMA16(a, b, c) __builtin_amdgcn_mfma_f32_16x16x32_bf16((a), (b), (c), 0, 0, 0)
; template <class Epi>
; DEVI void gemm_tile256b(const bf16_t* __restrict__ A, int lda, const bf16_t* __restrict__ Bt, int K,
;                         int m0, int n0, char* smem, Epi epi) {
;     ...
;     if (more) {
; #pragma unroll
;       for (int i = 0; i < 4; ++i) b0[i] = *(const bf16x8*)(bp + ((size_t)i * kb32 + kt * 2 + 2) * 512);
;     }
;     {
;       bf16x8 af[8];
; #pragma unroll
;       for (int i = 0; i < 8; ++i) af[i] = *(const bf16x8*)(base + ((a_rd + i * 2048) ^ 64));
; #pragma unroll
;       for (int mi = 0; mi < 8; ++mi)
; #pragma unroll
;         for (int ni = 0; ni < 4; ++ni) acc[mi][ni] = MFMA16(b1[ni], af[mi], acc[mi][ni]);
;     }
;     if (more) {
;       char* nb = smem + ((kt + 1) & 1) * 32768 + lds_w;
; #pragma unroll
;       for (int i = 0; i < 8; ++i) *(u32x4*)(nb + i * 4096) = ra[i];
;     }
;     __syncthreads();
	v_mfma_f32_16x16x32_bf16 v[118:121], v[150:153], v[174:177], v[118:121]
	s_waitcnt vmcnt(11)
	v_mfma_f32_16x16x32_bf16 v[114:117], v[154:157], v[174:177], v[114:117]
	s_waitcnt vmcnt(9)
	v_mfma_f32_16x16x32_bf16 v[106:109], v[158:161], v[174:177], v[106:109]
	s_waitcnt lgkmcnt(0)
	v_mfma_f32_16x16x32_bf16 v[102:105], v[146:149], v[178:181], v[102:105]
	v_mfma_f32_16x16x32_bf16 v[98:101], v[150:153], v[178:181], v[98:101]
	v_mfma_f32_16x16x32_bf16 v[82:85], v[154:157], v[178:181], v[82:85]
	s_nop 0
	v_mfma_f32_16x16x32_bf16 v[74:77], v[158:161], v[178:181], v[74:77]
	ds_read_b128 v[174:177], v0 offset:4096
	ds_read_b128 v[178:181], v0 offset:6144
	s_waitcnt lgkmcnt(1)
	v_mfma_f32_16x16x32_bf16 v[70:73], v[146:149], v[174:177], v[70:73]
	v_mfma_f32_16x16x32_bf16 v[66:69], v[150:153], v[174:177], v[66:69]
	s_and_b32 s13, s1, 0x8000
	v_mfma_f32_16x16x32_bf16 v[62:65], v[154:157], v[174:177], v[62:65]
	s_add_i32 s1, s1, 0x8000
	v_mfma_f32_16x16x32_bf16 v[54:57], v[158:161], v[174:177], v[54:57]
	v_lshl_add_u64 v[166:167], v[166:167], 0, s[60:61]
	s_cmp_eq_u32 s1, 0x80000
	s_waitcnt lgkmcnt(0)
	v_mfma_f32_16x16x32_bf16 v[42:45], v[146:149], v[178:181], v[42:45]
	v_mfma_f32_16x16x32_bf16 v[30:33], v[150:153], v[178:181], v[30:33]
	v_mfma_f32_16x16x32_bf16 v[38:41], v[154:157], v[178:181], v[38:41]
	v_mfma_f32_16x16x32_bf16 v[26:29], v[158:161], v[178:181], v[26:29]
	ds_read_b128 v[174:177], v0 offset:8192
	ds_read_b128 v[178:181], v0 offset:10240
	s_waitcnt lgkmcnt(1)
	v_mfma_f32_16x16x32_bf16 v[22:25], v[146:149], v[174:177], v[22:25]
	v_mfma_f32_16x16x32_bf16 v[18:21], v[150:153], v[174:177], v[18:21]
	v_mfma_f32_16x16x32_bf16 v[34:37], v[154:157], v[174:177], v[34:37]
	v_mfma_f32_16x16x32_bf16 v[46:49], v[158:161], v[174:177], v[46:49]
	s_waitcnt lgkmcnt(0)
	v_mfma_f32_16x16x32_bf16 v[50:53], v[146:149], v[178:181], v[50:53]
	v_mfma_f32_16x16x32_bf16 v[58:61], v[150:153], v[178:181], v[58:61]
	v_mfma_f32_16x16x32_bf16 v[94:97], v[154:157], v[178:181], v[94:97]
	v_mfma_f32_16x16x32_bf16 v[110:113], v[158:161], v[178:181], v[110:113]
	ds_read_b128 v[178:181], v0 offset:12288
	ds_read_b128 v[182:185], v0 offset:14336
	s_nop 0
	s_nop 0
	s_nop 0
	s_nop 0
	s_nop 0
	s_waitcnt lgkmcnt(1)
	v_mfma_f32_16x16x32_bf16 v[78:81], v[146:149], v[178:181], v[78:81]
	v_mfma_f32_16x16x32_bf16 v[90:93], v[150:153], v[178:181], v[90:93]
	v_mfma_f32_16x16x32_bf16 v[86:89], v[154:157], v[178:181], v[86:89]
	s_waitcnt vmcnt(0) lgkmcnt(0)
	s_barrier
	v_mfma_f32_16x16x32_bf16 v[142:145], v[158:161], v[178:181], v[142:145]
	v_mfma_f32_16x16x32_bf16 v[138:141], v[146:149], v[182:185], v[138:141]
	v_mfma_f32_16x16x32_bf16 v[134:137], v[150:153], v[182:185], v[134:137]
	v_mfma_f32_16x16x32_bf16 v[130:133], v[154:157], v[182:185], v[130:133]
	v_mfma_f32_16x16x32_bf16 v[126:129], v[158:161], v[182:185], v[126:129]
	s_cmp_eq_u32 s1, 0x80000
	s_cbranch_scc0 .LBB0_324
	v_add_u32_e32 v0, 32, v172
	ds_read_b128 v[146:149], v0 offset:32768
	ds_read_b128 v[150:153], v0 offset:34816
	s_waitcnt lgkmcnt(1)
	v_mfma_f32_16x16x32_bf16 v[122:125], v[10:13], v[146:149], v[122:125]
	v_mfma_f32_16x16x32_bf16 v[118:121], v[14:17], v[146:149], v[118:121]
	v_mfma_f32_16x16x32_bf16 v[114:117], v[6:9], v[146:149], v[114:117]
	v_mfma_f32_16x16x32_bf16 v[106:109], v[2:5], v[146:149], v[106:109]
	s_waitcnt lgkmcnt(0)
	v_mfma_f32_16x16x32_bf16 v[102:105], v[10:13], v[150:153], v[102:105]
	v_mfma_f32_16x16x32_bf16 v[98:101], v[14:17], v[150:153], v[98:101]
	v_mfma_f32_16x16x32_bf16 v[82:85], v[6:9], v[150:153], v[82:85]
	v_mfma_f32_16x16x32_bf16 v[74:77], v[2:5], v[150:153], v[74:77]
	ds_read_b128 v[146:149], v0 offset:36864
	ds_read_b128 v[150:153], v0 offset:38912
	s_waitcnt lgkmcnt(1)
	v_mfma_f32_16x16x32_bf16 v[70:73], v[10:13], v[146:149], v[70:73]
	v_mfma_f32_16x16x32_bf16 v[66:69], v[14:17], v[146:149], v[66:69]
	v_mfma_f32_16x16x32_bf16 v[62:65], v[6:9], v[146:149], v[62:65]
	v_mfma_f32_16x16x32_bf16 v[54:57], v[2:5], v[146:149], v[54:57]
	s_waitcnt lgkmcnt(0)
	v_mfma_f32_16x16x32_bf16 v[42:45], v[10:13], v[150:153], v[42:45]
	v_mfma_f32_16x16x32_bf16 v[30:33], v[14:17], v[150:153], v[30:33]
	v_mfma_f32_16x16x32_bf16 v[38:41], v[6:9], v[150:153], v[38:41]
	v_mfma_f32_16x16x32_bf16 v[26:29], v[2:5], v[150:153], v[26:29]
	ds_read_b128 v[146:149], v0 offset:40960
	ds_read_b128 v[150:153], v0 offset:43008
	s_waitcnt lgkmcnt(1)
	v_mfma_f32_16x16x32_bf16 v[22:25], v[10:13], v[146:149], v[22:25]
	v_mfma_f32_16x16x32_bf16 v[18:21], v[14:17], v[146:149], v[18:21]
	v_mfma_f32_16x16x32_bf16 v[34:37], v[6:9], v[146:149], v[34:37]
	v_mfma_f32_16x16x32_bf16 v[46:49], v[2:5], v[146:149], v[46:49]
	s_waitcnt lgkmcnt(0)
	v_mfma_f32_16x16x32_bf16 v[146:149], v[10:13], v[150:153], v[50:53]
	v_mfma_f32_16x16x32_bf16 v[154:157], v[14:17], v[150:153], v[58:61]
	s_nop 1
	ds_read_b128 v[50:53], v0 offset:45056
	ds_read_b128 v[58:61], v0 offset:47104
	v_add_u32_e32 v0, 32, v171
	s_waitcnt lgkmcnt(1)
	v_mfma_f32_16x16x32_bf16 v[164:167], v[10:13], v[50:53], v[78:81]
	s_nop 2
	v_add_co_u32_e32 v78, vcc, 0x7000, v162
	v_mfma_f32_16x16x32_bf16 v[172:175], v[14:17], v[50:53], v[90:93]
	s_nop 0
	v_addc_co_u32_e32 v79, vcc, 0, v163, vcc
	v_mfma_f32_16x16x32_bf16 v[176:179], v[6:9], v[50:53], v[86:89]
	v_mfma_f32_16x16x32_bf16 v[142:145], v[2:5], v[50:53], v[142:145]
	v_add_co_u32_e32 v50, vcc, 0xf000, v162
	s_nop 1
	v_addc_co_u32_e32 v51, vcc, 0, v163, vcc
	s_waitcnt lgkmcnt(0)
; #define MFMA16(a, b, c) __builtin_amdgcn_mfma_f32_16x16x32_bf16((a), (b), (c), 0, 0, 0)
; template <class Epi>
; DEVI void gemm_tile256b(const bf16_t* __restrict__ A, int lda, const bf16_t* __restrict__ Bt, int K,
;                         int m0, int n0, char* smem, Epi epi) {
;     ...
;     {
;       bf16x8 af[8];
; #pragma unroll
;       for (int i = 0; i < 8; ++i) af[i] = *(const bf16x8*)(base + ((a_rd + i * 2048) ^ 64));
; #pragma unroll
;       for (int mi = 0; mi < 8; ++mi)
; #pragma unroll
;         for (int ni = 0; ni < 4; ++ni) acc[mi][ni] = MFMA16(b1[ni], af[mi], acc[mi][ni]);
;     }
;     if (more) {
;       char* nb = smem + ((kt + 1) & 1) * 32768 + lds_w;
; #pragma unroll
;       for (int i = 0; i < 8; ++i) *(u32x4*)(nb + i * 4096) = ra[i];
;     }
;     __syncthreads();
;   }
; #pragma unroll
;   for (int mi = 0; mi < 8; ++mi)
; #pragma unroll
;     for (int ni = 0; ni < 4; ++ni)
;       epi(m0 + wm * 128 + mi * 16 + l15, n0 + wn * 64 + ni * 16 + quad * 4, acc[mi][ni]);
;   DEVI void operator()(int m, int n, f32x4 v) const {
;     if (m >= L) return;
;     float* h = hfrow(p, m) + n;
;     const float* src = (first && m >= 16) ? p.in[0] + (size_t)(m - 16) * 1024 + n : h;
;     f32x4 o = *(const f32x4*)src;
;     o = o * ALPHA + v;
;     *(f32x4*)h = o;
;   }
	v_mfma_f32_16x16x32_bf16 v[10:13], v[10:13], v[58:61], v[138:141]
	global_load_dwordx4 v[180:183], v[50:51], off offset:3072
	s_nop 1
	global_load_dwordx4 v[138:141], v[78:79], off offset:3072
	v_add_co_u32_e32 v78, vcc, 0x17000, v162
	v_mfma_f32_16x16x32_bf16 v[158:161], v[6:9], v[150:153], v[94:97]
	s_nop 0
	v_addc_co_u32_e32 v79, vcc, 0, v163, vcc
	v_mfma_f32_16x16x32_bf16 v[150:153], v[2:5], v[150:153], v[110:113]
	v_mfma_f32_16x16x32_bf16 v[134:137], v[14:17], v[58:61], v[134:137]
	ds_read_b128 v[14:17], v0 offset:32768
	v_mfma_f32_16x16x32_bf16 v[6:9], v[6:9], v[58:61], v[130:133]
	v_mfma_f32_16x16x32_bf16 v[2:5], v[2:5], v[58:61], v[126:129]
	v_add_co_u32_e32 v58, vcc, 0x1f000, v162
	s_nop 0
	global_load_dwordx4 v[130:133], v[78:79], off offset:3072
	v_addc_co_u32_e32 v59, vcc, 0, v163, vcc
	global_load_dwordx4 v[190:193], v[58:59], off offset:3072
	ds_read_b128 v[50:53], v0 offset:34816
	s_waitcnt vmcnt(2) lgkmcnt(1)
	v_mfma_f32_16x16x32_bf16 v[126:129], v[138:141], v[14:17], v[122:125]
	v_mfma_f32_16x16x32_bf16 v[122:125], v[180:183], v[14:17], v[118:121]
	s_waitcnt vmcnt(1)
	v_mfma_f32_16x16x32_bf16 v[118:121], v[130:133], v[14:17], v[114:117]
	s_waitcnt vmcnt(0)
	v_mfma_f32_16x16x32_bf16 v[114:117], v[190:193], v[14:17], v[106:109]
	s_waitcnt lgkmcnt(0)
	v_mfma_f32_16x16x32_bf16 v[110:113], v[138:141], v[50:53], v[102:105]
	v_mfma_f32_16x16x32_bf16 v[106:109], v[180:183], v[50:53], v[98:101]
	v_mfma_f32_16x16x32_bf16 v[102:105], v[130:133], v[50:53], v[82:85]
	v_mfma_f32_16x16x32_bf16 v[98:101], v[190:193], v[50:53], v[74:77]
	ds_read_b128 v[14:17], v0 offset:36864
	ds_read_b128 v[50:53], v0 offset:38912
	s_waitcnt lgkmcnt(1)
	v_mfma_f32_16x16x32_bf16 v[94:97], v[138:141], v[14:17], v[70:73]
	v_mfma_f32_16x16x32_bf16 v[90:93], v[180:183], v[14:17], v[66:69]
	v_mfma_f32_16x16x32_bf16 v[86:89], v[130:133], v[14:17], v[62:65]
	v_mfma_f32_16x16x32_bf16 v[82:85], v[190:193], v[14:17], v[54:57]
	s_waitcnt lgkmcnt(0)
	v_mfma_f32_16x16x32_bf16 v[66:69], v[190:193], v[50:53], v[26:29]
	ds_read_b128 v[14:17], v0 offset:40960
	s_nop 1
	ds_read_b128 v[26:29], v0 offset:43008
	v_mfma_f32_16x16x32_bf16 v[78:81], v[138:141], v[50:53], v[42:45]
	v_mfma_f32_16x16x32_bf16 v[74:77], v[180:183], v[50:53], v[30:33]
	v_mfma_f32_16x16x32_bf16 v[70:73], v[130:133], v[50:53], v[38:41]
	s_waitcnt lgkmcnt(1)
	v_mfma_f32_16x16x32_bf16 v[62:65], v[138:141], v[14:17], v[22:25]
	v_mfma_f32_16x16x32_bf16 v[58:61], v[180:183], v[14:17], v[18:21]
	v_mfma_f32_16x16x32_bf16 v[54:57], v[130:133], v[14:17], v[34:37]
	v_mfma_f32_16x16x32_bf16 v[50:53], v[190:193], v[14:17], v[46:49]
	s_waitcnt lgkmcnt(0)
	v_mfma_f32_16x16x32_bf16 v[46:49], v[138:141], v[26:29], v[146:149]
	ds_read_b128 v[14:17], v0 offset:45056
	s_nop 1
	ds_read_b128 v[146:149], v0 offset:47104
	v_and_b32_e32 v0, 0xffffff80, v168
	v_add_u32_e32 v0, s0, v0
	v_mfma_f32_16x16x32_bf16 v[42:45], v[180:183], v[26:29], v[154:157]
	s_movk_i32 s0, 0x4010
	s_waitcnt lgkmcnt(0)
	s_barrier
	v_mfma_f32_16x16x32_bf16 v[38:41], v[130:133], v[26:29], v[158:161]
	v_mfma_f32_16x16x32_bf16 v[34:37], v[190:193], v[26:29], v[150:153]
	v_mfma_f32_16x16x32_bf16 v[30:33], v[138:141], v[14:17], v[164:167]
	v_mfma_f32_16x16x32_bf16 v[26:29], v[180:183], v[14:17], v[172:175]
	v_mfma_f32_16x16x32_bf16 v[22:25], v[130:133], v[14:17], v[176:179]
	v_mfma_f32_16x16x32_bf16 v[18:21], v[190:193], v[14:17], v[142:145]
	v_mfma_f32_16x16x32_bf16 v[14:17], v[138:141], v[146:149], v[10:13]
	v_mfma_f32_16x16x32_bf16 v[10:13], v[180:183], v[146:149], v[134:137]
	v_mfma_f32_16x16x32_bf16 v[6:9], v[130:133], v[146:149], v[6:9]
	v_and_or_b32 v132, v168, 15, v0
	v_lshl_or_b32 v130, v169, 2, v170
	v_cmp_gt_i32_e32 vcc, s0, v132
	v_mfma_f32_16x16x32_bf16 v[2:5], v[190:193], v[146:149], v[2:5]
	v_ashrrev_i32_e32 v131, 31, v130
	s_and_saveexec_b64 s[0:1], vcc
	s_cbranch_execz .LBB0_327
	v_lshlrev_b32_e32 v134, 10, v132
	v_add_u32_e32 v136, -16, v132
	v_mov_b32_e32 v137, v1
	v_ashrrev_i32_e32 v135, 31, v134
	v_lshlrev_b64 v[136:137], 12, v[136:137]
	v_lshl_add_u64 v[134:135], v[134:135], 2, s[10:11]
	v_lshl_add_u64 v[136:137], s[26:27], 0, v[136:137]
	v_cmp_gt_i32_e32 vcc, 16, v132
	s_nop 1
	v_cndmask_b32_e32 v135, v137, v135, vcc
	v_cndmask_b32_e32 v134, v136, v134, vcc
	v_lshl_add_u64 v[138:139], v[130:131], 2, v[134:135]
	global_load_dwordx4 v[134:137], v[138:139], off
	s_waitcnt vmcnt(0)
	v_pk_fma_f32 v[128:129], v[136:137], s[66:67], v[128:129] op_sel_hi:[1,0,1]
	v_pk_fma_f32 v[126:127], v[134:135], s[66:67], v[126:127] op_sel_hi:[1,0,1]
	global_store_dwordx4 v[138:139], v[126:129], off
	global_load_dwordx4 v[126:129], v[138:139], off offset:64
	s_waitcnt vmcnt(0)
	v_pk_fma_f32 v[124:125], v[128:129], s[66:67], v[124:125] op_sel_hi:[1,0,1]
	v_pk_fma_f32 v[122:123], v[126:127], s[66:67], v[122:123] op_sel_hi:[1,0,1]
	global_store_dwordx4 v[138:139], v[122:125], off offset:64
	global_load_dwordx4 v[122:125], v[138:139], off offset:128
	s_waitcnt vmcnt(0)
	v_pk_fma_f32 v[120:121], v[124:125], s[66:67], v[120:121] op_sel_hi:[1,0,1]
	v_pk_fma_f32 v[118:119], v[122:123], s[66:67], v[118:119] op_sel_hi:[1,0,1]
	global_store_dwordx4 v[138:139], v[118:121], off offset:128
	global_load_dwordx4 v[118:121], v[138:139], off offset:192
	s_waitcnt vmcnt(0)
	v_pk_fma_f32 v[116:117], v[120:121], s[66:67], v[116:117] op_sel_hi:[1,0,1]
	v_pk_fma_f32 v[114:115], v[118:119], s[66:67], v[114:115] op_sel_hi:[1,0,1]
	global_store_dwordx4 v[138:139], v[114:117], off offset:192

; #define MFMA16(a, b, c) __builtin_amdgcn_mfma_f32_16x16x32_bf16((a), (b), (c), 0, 0, 0)
; template <class Epi>
; DEVI void gemm_tile256b(const bf16_t* __restrict__ A, int lda, const bf16_t* __restrict__ Bt, int K,
;                         int m0, int n0, char* smem, Epi epi) {
;     ...
;   for (int kt = 0; kt < nk; ++kt) {
;     const char* base = smem + (kt & 1) * 32768;
;     const bool more = kt + 1 < nk;
;     if (more) {
; #pragma unroll
;       for (int i = 0; i < 8; ++i) ra[i] = *(const u32x4*)(ag + (size_t)(i * 32) * lda + (kt + 1) * 64);
;     }
; #pragma unroll
;     for (int i = 0; i < 4; ++i) b1[i] = *(const bf16x8*)(bp + ((size_t)i * kb32 + kt * 2 + 1) * 512);
;     {
;       bf16x8 af[8];
; #pragma unroll
;       for (int i = 0; i < 8; ++i) af[i] = *(const bf16x8*)(base + a_rd + i * 2048);
; #pragma unroll
;       for (int mi = 0; mi < 8; ++mi)
; #pragma unroll
;         for (int ni = 0; ni < 4; ++ni) acc[mi][ni] = MFMA16(b0[ni], af[mi], acc[mi][ni]);
;     }
;     if (more) {
; #pragma unroll
;       for (int i = 0; i < 4; ++i) b0[i] = *(const bf16x8*)(bp + ((size_t)i * kb32 + kt * 2 + 2) * 512);
;     }
;     {
;       bf16x8 af[8];
; #pragma unroll
;       for (int i = 0; i < 8; ++i) af[i] = *(const bf16x8*)(base + ((a_rd + i * 2048) ^ 64));
; #pragma unroll
;       for (int mi = 0; mi < 8; ++mi)
; #pragma unroll
;         for (int ni = 0; ni < 4; ++ni) acc[mi][ni] = MFMA16(b1[ni], af[mi], acc[mi][ni]);
;     }
;     if (more) {
;       char* nb = smem + ((kt + 1) & 1) * 32768 + lds_w;
; #pragma unroll
;       for (int i = 0; i < 8; ++i) *(u32x4*)(nb + i * 4096) = ra[i];
.LBB0_363:
	s_add_i32 s13, s1, 0xffff8000
	s_and_b32 s13, s13, 0x8000
	s_add_i32 s13, s13, 32
	v_add_u32_e32 v154, s13, v172
	ds_read_b128 v[146:149], v154
	ds_read_b128 v[150:153], v154 offset:2048
	s_mov_b32 s16, 0x2680000
	v_add_u32_e32 v173, s13, v170
	s_waitcnt vmcnt(3) lgkmcnt(1)
	v_mfma_f32_16x16x32_bf16 v[134:137], v[10:13], v[146:149], v[134:137]
	s_and_b32 s13, s1, 0x8000
	s_add_i32 s1, s1, 0x8000
	v_lshl_add_u64 v[166:167], v[166:167], 0, s[60:61]
	s_waitcnt vmcnt(2)
	v_mfma_f32_16x16x32_bf16 v[130:133], v[14:17], v[146:149], v[130:133]
	s_cmp_eq_u32 s1, 0x80000
	s_waitcnt vmcnt(1)
	v_mfma_f32_16x16x32_bf16 v[126:129], v[2:5], v[146:149], v[126:129]
	s_waitcnt vmcnt(0)
	v_mfma_f32_16x16x32_bf16 v[122:125], v[6:9], v[146:149], v[122:125]
	s_waitcnt lgkmcnt(0)
	v_mfma_f32_16x16x32_bf16 v[114:117], v[10:13], v[150:153], v[114:117]
	v_mfma_f32_16x16x32_bf16 v[110:113], v[14:17], v[150:153], v[110:113]
	v_mfma_f32_16x16x32_bf16 v[106:109], v[2:5], v[150:153], v[106:109]
	v_mfma_f32_16x16x32_bf16 v[102:105], v[6:9], v[150:153], v[102:105]
	ds_read_b128 v[146:149], v154 offset:4096
	ds_read_b128 v[150:153], v154 offset:6144
	s_waitcnt lgkmcnt(1)
	v_mfma_f32_16x16x32_bf16 v[98:101], v[10:13], v[146:149], v[98:101]
	v_mfma_f32_16x16x32_bf16 v[94:97], v[14:17], v[146:149], v[94:97]
	v_mfma_f32_16x16x32_bf16 v[86:89], v[2:5], v[146:149], v[86:89]
	v_mfma_f32_16x16x32_bf16 v[82:85], v[6:9], v[146:149], v[82:85]
	s_waitcnt lgkmcnt(0)
	v_mfma_f32_16x16x32_bf16 v[74:77], v[10:13], v[150:153], v[74:77]
	v_mfma_f32_16x16x32_bf16 v[70:73], v[14:17], v[150:153], v[70:73]
	v_mfma_f32_16x16x32_bf16 v[62:65], v[2:5], v[150:153], v[62:65]
	v_mfma_f32_16x16x32_bf16 v[66:69], v[6:9], v[150:153], v[66:69]
	ds_read_b128 v[146:149], v154 offset:8192
	ds_read_b128 v[150:153], v154 offset:10240
	s_waitcnt lgkmcnt(1)
	v_mfma_f32_16x16x32_bf16 v[46:49], v[10:13], v[146:149], v[46:49]
	v_mfma_f32_16x16x32_bf16 v[50:53], v[14:17], v[146:149], v[50:53]
	v_mfma_f32_16x16x32_bf16 v[58:61], v[2:5], v[146:149], v[58:61]
	v_mfma_f32_16x16x32_bf16 v[54:57], v[6:9], v[146:149], v[54:57]
	s_waitcnt lgkmcnt(0)
	v_mfma_f32_16x16x32_bf16 v[26:29], v[10:13], v[150:153], v[26:29]
	v_mfma_f32_16x16x32_bf16 v[22:25], v[14:17], v[150:153], v[22:25]
	v_mfma_f32_16x16x32_bf16 v[18:21], v[2:5], v[150:153], v[18:21]
	v_mfma_f32_16x16x32_bf16 v[42:45], v[6:9], v[150:153], v[42:45]
	ds_read_b128 v[146:149], v154 offset:12288
	ds_read_b128 v[150:153], v154 offset:14336
	v_lshl_add_u64 v[154:155], v[164:165], 0, s[28:29]
	v_add_co_u32_e32 v156, vcc, s16, v154
	s_mov_b32 s16, 0x2688000
	s_nop 0
	v_addc_co_u32_e32 v157, vcc, 0, v155, vcc
	v_add_co_u32_e32 v158, vcc, s16, v154
	s_waitcnt lgkmcnt(1)
	v_mfma_f32_16x16x32_bf16 v[34:37], v[10:13], v[146:149], v[34:37]
	v_addc_co_u32_e32 v159, vcc, 0, v155, vcc
	s_mov_b32 s16, 0x2690000
	v_mfma_f32_16x16x32_bf16 v[38:41], v[14:17], v[146:149], v[38:41]
	v_add_co_u32_e32 v160, vcc, s16, v154
	s_mov_b32 s16, 0x2698000
	v_mfma_f32_16x16x32_bf16 v[30:33], v[2:5], v[146:149], v[30:33]
	v_addc_co_u32_e32 v161, vcc, 0, v155, vcc
	v_add_co_u32_e32 v182, vcc, s16, v154
	v_mfma_f32_16x16x32_bf16 v[142:145], v[6:9], v[146:149], v[142:145]
	global_load_dwordx4 v[146:149], v[156:157], off offset:1024
	v_addc_co_u32_e32 v183, vcc, 0, v155, vcc
	s_waitcnt lgkmcnt(0)
	v_mfma_f32_16x16x32_bf16 v[138:141], v[10:13], v[150:153], v[138:141]
	ds_read_b128 v[174:177], v173
	ds_read_b128 v[178:181], v173 offset:2048
	global_load_dwordx4 v[10:13], v[156:157], off offset:2048
	v_mfma_f32_16x16x32_bf16 v[118:121], v[14:17], v[150:153], v[118:121]
	s_nop 0
	v_mfma_f32_16x16x32_bf16 v[90:93], v[2:5], v[150:153], v[90:93]
	s_nop 0
	v_mfma_f32_16x16x32_bf16 v[78:81], v[6:9], v[150:153], v[78:81]
	global_load_dwordx4 v[150:153], v[158:159], off offset:1024
	global_load_dwordx4 v[14:17], v[158:159], off offset:2048
	global_load_dwordx4 v[154:157], v[160:161], off offset:1024
	global_load_dwordx4 v[2:5], v[160:161], off offset:2048
	s_nop 0
	global_load_dwordx4 v[158:161], v[182:183], off offset:1024
	global_load_dwordx4 v[6:9], v[182:183], off offset:2048
	v_lshrrev_b32_e32 v195, 6, v206
	v_lshl_add_u64 v[190:191], v[166:167], 0, s[28:29]
	v_lshrrev_b32_e32 v194, 3, v206
	v_readfirstlane_b32 s99, v195
	v_and_b32_e32 v194, 7, v194
	s_and_b32 s98, s1, 0x8000
	s_xor_b32 s98, s98, 0x8000
	v_lshlrev_b32_e32 v194, 4, v194
	s_lshl_b32 s99, s99, 10
	v_xor_b32_e32 v190, v194, v190
	s_add_u32 s98, s98, s99
	s_add_u32 s98, s98, 32
	s_mov_b32 s101, 0
	s_mov_b32 s100, 0x0
	v_lshl_add_u64 v[192:193], v[190:191], 0, s[100:101]
	s_mov_b32 m0, s98
	s_nop 0
	global_load_lds_dwordx4 v[192:193], off
	s_add_u32 s100, s54, 0x0
	v_lshl_add_u64 v[192:193], v[190:191], 0, s[100:101]
	s_add_u32 m0, s98, 0x1000
	s_nop 0
	global_load_lds_dwordx4 v[192:193], off
	s_add_u32 s100, s53, 0x0
	v_lshl_add_u64 v[192:193], v[190:191], 0, s[100:101]
	s_add_u32 m0, s98, 0x2000
	s_nop 0
	global_load_lds_dwordx4 v[192:193], off
	s_add_u32 s100, s52, 0x0
	v_lshl_add_u64 v[192:193], v[190:191], 0, s[100:101]
	s_add_u32 m0, s98, 0x3000
	s_nop 0
	global_load_lds_dwordx4 v[192:193], off
	s_add_u32 s100, s56, 0x0
	v_lshl_add_u64 v[192:193], v[190:191], 0, s[100:101]
	s_add_u32 m0, s98, 0x4000
	s_nop 0
	global_load_lds_dwordx4 v[192:193], off
	s_add_u32 s100, s57, 0x0
	v_lshl_add_u64 v[192:193], v[190:191], 0, s[100:101]
	s_add_u32 m0, s98, 0x5000
	s_nop 0
	global_load_lds_dwordx4 v[192:193], off
	s_add_u32 s100, s3, 0x0
	v_lshl_add_u64 v[192:193], v[190:191], 0, s[100:101]
	s_add_u32 m0, s98, 0x6000
	s_nop 0
	global_load_lds_dwordx4 v[192:193], off
	s_add_u32 s100, s19, 0x0
	v_lshl_add_u64 v[192:193], v[190:191], 0, s[100:101]
	s_add_u32 m0, s98, 0x7000
	s_nop 0
	global_load_lds_dwordx4 v[192:193], off
	s_waitcnt vmcnt(15) lgkmcnt(1)
; #define MFMA16(a, b, c) __builtin_amdgcn_mfma_f32_16x16x32_bf16((a), (b), (c), 0, 0, 0)
; template <class Epi>
; DEVI void gemm_tile256b(const bf16_t* __restrict__ A, int lda, const bf16_t* __restrict__ Bt, int K,
;                         int m0, int n0, char* smem, Epi epi) {
;     ...
;     if (more) {
; #pragma unroll
;       for (int i = 0; i < 4; ++i) b0[i] = *(const bf16x8*)(bp + ((size_t)i * kb32 + kt * 2 + 2) * 512);
;     }
;     {
;       bf16x8 af[8];
; #pragma unroll
;       for (int i = 0; i < 8; ++i) af[i] = *(const bf16x8*)(base + ((a_rd + i * 2048) ^ 64));
; #pragma unroll
;       for (int mi = 0; mi < 8; ++mi)
; #pragma unroll
;         for (int ni = 0; ni < 4; ++ni) acc[mi][ni] = MFMA16(b1[ni], af[mi], acc[mi][ni]);
;     }
;     if (more) {
;       char* nb = smem + ((kt + 1) & 1) * 32768 + lds_w;
; #pragma unroll
;       for (int i = 0; i < 8; ++i) *(u32x4*)(nb + i * 4096) = ra[i];
;     }
;     __syncthreads();
	v_mfma_f32_16x16x32_bf16 v[134:137], v[146:149], v[174:177], v[134:137]
	s_waitcnt vmcnt(13)
	v_mfma_f32_16x16x32_bf16 v[130:133], v[150:153], v[174:177], v[130:133]
	s_waitcnt vmcnt(11)
	v_mfma_f32_16x16x32_bf16 v[126:129], v[154:157], v[174:177], v[126:129]
	s_waitcnt vmcnt(9)
	v_mfma_f32_16x16x32_bf16 v[122:125], v[158:161], v[174:177], v[122:125]
	s_waitcnt lgkmcnt(0)
	v_mfma_f32_16x16x32_bf16 v[114:117], v[146:149], v[178:181], v[114:117]
	v_lshl_add_u64 v[164:165], v[164:165], 0, s[64:65]
	v_mfma_f32_16x16x32_bf16 v[110:113], v[150:153], v[178:181], v[110:113]
	v_mfma_f32_16x16x32_bf16 v[106:109], v[154:157], v[178:181], v[106:109]
	v_mfma_f32_16x16x32_bf16 v[102:105], v[158:161], v[178:181], v[102:105]
	ds_read_b128 v[174:177], v173 offset:4096
	ds_read_b128 v[178:181], v173 offset:6144
	s_waitcnt lgkmcnt(1)
	v_mfma_f32_16x16x32_bf16 v[98:101], v[146:149], v[174:177], v[98:101]
	v_mfma_f32_16x16x32_bf16 v[94:97], v[150:153], v[174:177], v[94:97]
	v_mfma_f32_16x16x32_bf16 v[86:89], v[154:157], v[174:177], v[86:89]
	v_mfma_f32_16x16x32_bf16 v[82:85], v[158:161], v[174:177], v[82:85]
	s_waitcnt lgkmcnt(0)
	v_mfma_f32_16x16x32_bf16 v[74:77], v[146:149], v[178:181], v[74:77]
	v_mfma_f32_16x16x32_bf16 v[70:73], v[150:153], v[178:181], v[70:73]
	v_mfma_f32_16x16x32_bf16 v[62:65], v[154:157], v[178:181], v[62:65]
	v_mfma_f32_16x16x32_bf16 v[66:69], v[158:161], v[178:181], v[66:69]
	ds_read_b128 v[178:181], v173 offset:8192
	ds_read_b128 v[182:185], v173 offset:10240
	s_waitcnt lgkmcnt(1)
	v_mfma_f32_16x16x32_bf16 v[46:49], v[146:149], v[178:181], v[46:49]
	v_mfma_f32_16x16x32_bf16 v[50:53], v[150:153], v[178:181], v[50:53]
	v_mfma_f32_16x16x32_bf16 v[58:61], v[154:157], v[178:181], v[58:61]
	v_mfma_f32_16x16x32_bf16 v[54:57], v[158:161], v[178:181], v[54:57]
	s_waitcnt lgkmcnt(0)
	v_mfma_f32_16x16x32_bf16 v[26:29], v[146:149], v[182:185], v[26:29]
	v_mfma_f32_16x16x32_bf16 v[22:25], v[150:153], v[182:185], v[22:25]
	v_mfma_f32_16x16x32_bf16 v[18:21], v[154:157], v[182:185], v[18:21]
	v_mfma_f32_16x16x32_bf16 v[42:45], v[158:161], v[182:185], v[42:45]
	ds_read_b128 v[178:181], v173 offset:12288
	ds_read_b128 v[182:185], v173 offset:14336
	s_nop 0
	s_nop 0
	s_nop 0
	s_nop 0
	s_nop 0
	s_waitcnt lgkmcnt(1)
	v_mfma_f32_16x16x32_bf16 v[34:37], v[146:149], v[178:181], v[34:37]
	v_mfma_f32_16x16x32_bf16 v[38:41], v[150:153], v[178:181], v[38:41]
	v_mfma_f32_16x16x32_bf16 v[30:33], v[154:157], v[178:181], v[30:33]
	s_waitcnt vmcnt(0) lgkmcnt(0)
	s_barrier
	v_mfma_f32_16x16x32_bf16 v[142:145], v[158:161], v[178:181], v[142:145]
	v_mfma_f32_16x16x32_bf16 v[138:141], v[146:149], v[182:185], v[138:141]
	v_mfma_f32_16x16x32_bf16 v[118:121], v[150:153], v[182:185], v[118:121]
	v_mfma_f32_16x16x32_bf16 v[90:93], v[154:157], v[182:185], v[90:93]
	v_mfma_f32_16x16x32_bf16 v[78:81], v[158:161], v[182:185], v[78:81]
	s_cmp_eq_u32 s1, 0x80000
	s_cbranch_scc0 .LBB0_363
	v_add_u32_e32 v171, 32, v172
	ds_read_b128 v[146:149], v171 offset:32768
	s_movk_i32 s1, 0x7000
	v_add_u32_e32 v170, 32, v170
	s_waitcnt lgkmcnt(0)
	v_mfma_f32_16x16x32_bf16 v[134:137], v[10:13], v[146:149], v[134:137]
	v_mfma_f32_16x16x32_bf16 v[130:133], v[14:17], v[146:149], v[130:133]
	v_mfma_f32_16x16x32_bf16 v[126:129], v[2:5], v[146:149], v[126:129]
	v_mfma_f32_16x16x32_bf16 v[122:125], v[6:9], v[146:149], v[122:125]
	ds_read_b128 v[146:149], v171 offset:34816
	s_waitcnt lgkmcnt(0)
	v_mfma_f32_16x16x32_bf16 v[114:117], v[10:13], v[146:149], v[114:117]
	v_mfma_f32_16x16x32_bf16 v[150:153], v[14:17], v[146:149], v[110:113]
	v_mfma_f32_16x16x32_bf16 v[154:157], v[2:5], v[146:149], v[106:109]
	v_mfma_f32_16x16x32_bf16 v[146:149], v[6:9], v[146:149], v[102:105]
	s_nop 2
	ds_read_b128 v[102:105], v171 offset:36864
	s_waitcnt lgkmcnt(0)
	v_mfma_f32_16x16x32_bf16 v[164:167], v[14:17], v[102:105], v[94:97]
	s_nop 2
	ds_read_b128 v[94:97], v171 offset:38912
	s_waitcnt lgkmcnt(0)
	v_mfma_f32_16x16x32_bf16 v[74:77], v[10:13], v[94:97], v[74:77]
	v_mfma_f32_16x16x32_bf16 v[70:73], v[14:17], v[94:97], v[70:73]
	v_mfma_f32_16x16x32_bf16 v[62:65], v[2:5], v[94:97], v[62:65]
	v_mfma_f32_16x16x32_bf16 v[66:69], v[6:9], v[94:97], v[66:69]
	ds_read_b128 v[94:97], v171 offset:40960
	s_waitcnt lgkmcnt(0)
	v_mfma_f32_16x16x32_bf16 v[176:179], v[6:9], v[94:97], v[54:57]
	s_nop 2
	ds_read_b128 v[54:57], v171 offset:43008
	s_waitcnt lgkmcnt(0)
	v_mfma_f32_16x16x32_bf16 v[180:183], v[6:9], v[54:57], v[42:45]
	s_nop 2
	ds_read_b128 v[42:45], v171 offset:45056
	s_waitcnt lgkmcnt(0)
	v_mfma_f32_16x16x32_bf16 v[198:201], v[2:5], v[42:45], v[30:33]
	s_nop 2
	ds_read_b128 v[30:33], v171 offset:47104
	v_mfma_f32_16x16x32_bf16 v[158:161], v[10:13], v[102:105], v[98:101]
	v_mfma_f32_16x16x32_bf16 v[46:49], v[10:13], v[94:97], v[46:49]
	v_mfma_f32_16x16x32_bf16 v[50:53], v[14:17], v[94:97], v[50:53]
	v_mfma_f32_16x16x32_bf16 v[26:29], v[10:13], v[54:57], v[26:29]
	v_mfma_f32_16x16x32_bf16 v[22:25], v[14:17], v[54:57], v[22:25]
	v_mfma_f32_16x16x32_bf16 v[190:193], v[10:13], v[42:45], v[34:37]
	v_mfma_f32_16x16x32_bf16 v[194:197], v[14:17], v[42:45], v[38:41]
	s_waitcnt lgkmcnt(0)
; #define MFMA16(a, b, c) __builtin_amdgcn_mfma_f32_16x16x32_bf16((a), (b), (c), 0, 0, 0)
; template <class Epi>
; DEVI void gemm_tile256b(const bf16_t* __restrict__ A, int lda, const bf16_t* __restrict__ Bt, int K,
;                         int m0, int n0, char* smem, Epi epi) {
;     ...
;     {
;       bf16x8 af[8];
; #pragma unroll
;       for (int i = 0; i < 8; ++i) af[i] = *(const bf16x8*)(base + ((a_rd + i * 2048) ^ 64));
; #pragma unroll
;       for (int mi = 0; mi < 8; ++mi)
; #pragma unroll
;         for (int ni = 0; ni < 4; ++ni) acc[mi][ni] = MFMA16(b1[ni], af[mi], acc[mi][ni]);
;     }
;     if (more) {
;       char* nb = smem + ((kt + 1) & 1) * 32768 + lds_w;
; #pragma unroll
;       for (int i = 0; i < 8; ++i) *(u32x4*)(nb + i * 4096) = ra[i];
;     }
;     __syncthreads();
;   }
; #pragma unroll
;   for (int mi = 0; mi < 8; ++mi)
; #pragma unroll
;     for (int ni = 0; ni < 4; ++ni)
;       epi(m0 + wm * 128 + mi * 16 + l15, n0 + wn * 64 + ni * 16 + quad * 4, acc[mi][ni]);
;   DEVI void operator()(int m, int n, f32x4 v) const {
;     if (m >= L) return;
;     *(u32x2*)(z + (size_t)m * 1024 + n) = u32x2{pack2(v[0], v[1]), pack2(v[2], v[3])};
;   }
	v_mfma_f32_16x16x32_bf16 v[10:13], v[10:13], v[30:33], v[138:141]
	v_mfma_f32_16x16x32_bf16 v[138:141], v[14:17], v[30:33], v[118:121]
	v_add_co_u32_e32 v14, vcc, s1, v162
	s_mov_b32 s1, 0xf000
	s_nop 0
	v_addc_co_u32_e32 v15, vcc, 0, v163, vcc
	global_load_dwordx4 v[14:17], v[14:15], off offset:3072
	v_mfma_f32_16x16x32_bf16 v[82:85], v[6:9], v[102:105], v[82:85]
	v_add_co_u32_e32 v34, vcc, s1, v162
	s_mov_b32 s1, 0x17000
	v_mfma_f32_16x16x32_bf16 v[142:145], v[6:9], v[42:45], v[142:145]
	v_addc_co_u32_e32 v35, vcc, 0, v163, vcc
	global_load_dwordx4 v[202:205], v[34:35], off offset:3072
	v_mfma_f32_16x16x32_bf16 v[226:229], v[6:9], v[30:33], v[78:81]
	ds_read_b128 v[6:9], v170 offset:32768
	v_mfma_f32_16x16x32_bf16 v[86:89], v[2:5], v[102:105], v[86:89]
	v_mfma_f32_16x16x32_bf16 v[172:175], v[2:5], v[94:97], v[58:61]
	v_mfma_f32_16x16x32_bf16 v[18:21], v[2:5], v[54:57], v[18:21]
	v_mfma_f32_16x16x32_bf16 v[2:5], v[2:5], v[30:33], v[90:93]
	v_add_co_u32_e32 v30, vcc, s1, v162
	s_mov_b32 s1, 0x1f000
	s_nop 0
	v_addc_co_u32_e32 v31, vcc, 0, v163, vcc
	s_waitcnt vmcnt(1) lgkmcnt(0)
	v_mfma_f32_16x16x32_bf16 v[110:113], v[14:17], v[6:9], v[134:137]
	s_nop 2
	global_load_dwordx4 v[134:137], v[30:31], off offset:3072
	v_add_co_u32_e32 v30, vcc, s1, v162
	s_waitcnt vmcnt(1)
	v_mfma_f32_16x16x32_bf16 v[106:109], v[202:205], v[6:9], v[130:133]
	v_addc_co_u32_e32 v31, vcc, 0, v163, vcc
	global_load_dwordx4 v[230:233], v[30:31], off offset:3072
	s_waitcnt vmcnt(1)
	v_mfma_f32_16x16x32_bf16 v[102:105], v[134:137], v[6:9], v[126:129]
	v_lshl_or_b32 v130, v168, 2, v169
	v_ashrrev_i32_e32 v131, 31, v130
	s_waitcnt vmcnt(0)
	v_mfma_f32_16x16x32_bf16 v[98:101], v[230:233], v[6:9], v[122:125]
	ds_read_b128 v[6:9], v170 offset:34816
	s_waitcnt lgkmcnt(0)
	v_mfma_f32_16x16x32_bf16 v[126:129], v[14:17], v[6:9], v[114:117]
	v_mfma_f32_16x16x32_bf16 v[122:125], v[202:205], v[6:9], v[150:153]
	v_mfma_f32_16x16x32_bf16 v[118:121], v[134:137], v[6:9], v[154:157]
	v_mfma_f32_16x16x32_bf16 v[114:117], v[230:233], v[6:9], v[146:149]
	ds_read_b128 v[6:9], v170 offset:36864
	s_waitcnt lgkmcnt(0)
	v_mfma_f32_16x16x32_bf16 v[94:97], v[14:17], v[6:9], v[158:161]
	v_mfma_f32_16x16x32_bf16 v[90:93], v[202:205], v[6:9], v[164:167]
	v_mfma_f32_16x16x32_bf16 v[86:89], v[134:137], v[6:9], v[86:89]
	v_mfma_f32_16x16x32_bf16 v[82:85], v[230:233], v[6:9], v[82:85]
	ds_read_b128 v[6:9], v170 offset:38912
	s_waitcnt lgkmcnt(0)
	v_mfma_f32_16x16x32_bf16 v[78:81], v[14:17], v[6:9], v[74:77]
	v_mfma_f32_16x16x32_bf16 v[74:77], v[202:205], v[6:9], v[70:73]
	v_mfma_f32_16x16x32_bf16 v[70:73], v[134:137], v[6:9], v[62:65]
	v_mfma_f32_16x16x32_bf16 v[66:69], v[230:233], v[6:9], v[66:69]
	ds_read_b128 v[6:9], v170 offset:40960
	s_waitcnt lgkmcnt(0)
	v_mfma_f32_16x16x32_bf16 v[62:65], v[14:17], v[6:9], v[46:49]
	v_mfma_f32_16x16x32_bf16 v[58:61], v[202:205], v[6:9], v[50:53]
	v_mfma_f32_16x16x32_bf16 v[54:57], v[134:137], v[6:9], v[172:175]
	v_mfma_f32_16x16x32_bf16 v[50:53], v[230:233], v[6:9], v[176:179]
	ds_read_b128 v[6:9], v170 offset:43008
	s_waitcnt lgkmcnt(0)
	v_mfma_f32_16x16x32_bf16 v[46:49], v[14:17], v[6:9], v[26:29]
	v_mfma_f32_16x16x32_bf16 v[42:45], v[202:205], v[6:9], v[22:25]
	v_mfma_f32_16x16x32_bf16 v[38:41], v[134:137], v[6:9], v[18:21]
	v_mfma_f32_16x16x32_bf16 v[34:37], v[230:233], v[6:9], v[180:183]
	ds_read_b128 v[6:9], v170 offset:45056
	s_waitcnt lgkmcnt(0)
	v_mfma_f32_16x16x32_bf16 v[18:21], v[230:233], v[6:9], v[142:145]
	s_nop 2
	ds_read_b128 v[142:145], v170 offset:47104
	s_waitcnt lgkmcnt(0)
	v_mfma_f32_16x16x32_bf16 v[30:33], v[14:17], v[6:9], v[190:193]
	s_barrier
	v_mfma_f32_16x16x32_bf16 v[14:17], v[14:17], v[142:145], v[10:13]
	s_nop 2
	v_and_b32_e32 v10, 0xffffff80, v0
	v_add_u32_e32 v10, s0, v10
	v_mfma_f32_16x16x32_bf16 v[26:29], v[202:205], v[6:9], v[194:197]
	v_and_or_b32 v132, v0, 15, v10
	s_movk_i32 s0, 0x4010
	v_cmp_gt_i32_e32 vcc, s0, v132
	v_mfma_f32_16x16x32_bf16 v[22:25], v[134:137], v[6:9], v[198:201]
	v_mfma_f32_16x16x32_bf16 v[6:9], v[202:205], v[142:145], v[138:141]
	v_mfma_f32_16x16x32_bf16 v[2:5], v[134:137], v[142:145], v[2:5]
	v_mfma_f32_16x16x32_bf16 v[10:13], v[230:233], v[142:145], v[226:229]
	s_and_saveexec_b64 s[0:1], vcc
	s_cbranch_execz .LBB0_366
	v_ashrrev_i32_e32 v133, 31, v132
	v_lshlrev_b64 v[134:135], 11, v[132:133]
	v_lshl_add_u64 v[134:135], s[10:11], 0, v[134:135]
	v_cvt_pk_bf16_f32 v110, v110, v111
	v_cvt_pk_bf16_f32 v111, v112, v113
	v_lshl_add_u64 v[112:113], v[130:131], 1, v[134:135]
	v_cvt_pk_bf16_f32 v106, v106, v107
	v_cvt_pk_bf16_f32 v107, v108, v109
	v_cvt_pk_bf16_f32 v102, v102, v103
	v_cvt_pk_bf16_f32 v103, v104, v105
	v_cvt_pk_bf16_f32 v98, v98, v99
	v_cvt_pk_bf16_f32 v99, v100, v101
	global_store_dwordx2 v[112:113], v[110:111], off
	global_store_dwordx2 v[112:113], v[106:107], off offset:32
	global_store_dwordx2 v[112:113], v[102:103], off offset:64
	global_store_dwordx2 v[112:113], v[98:99], off offset:96

; #define MFMA16(a, b, c) __builtin_amdgcn_mfma_f32_16x16x32_bf16((a), (b), (c), 0, 0, 0)
; template <class Epi>
; DEVI void gemm_tile256b(const bf16_t* __restrict__ A, int lda, const bf16_t* __restrict__ Bt, int K,
;                         int m0, int n0, char* smem, Epi epi) {
;     ...
;   for (int kt = 0; kt < nk; ++kt) {
;     const char* base = smem + (kt & 1) * 32768;
;     const bool more = kt + 1 < nk;
;     if (more) {
; #pragma unroll
;       for (int i = 0; i < 8; ++i) ra[i] = *(const u32x4*)(ag + (size_t)(i * 32) * lda + (kt + 1) * 64);
;     }
; #pragma unroll
;     for (int i = 0; i < 4; ++i) b1[i] = *(const bf16x8*)(bp + ((size_t)i * kb32 + kt * 2 + 1) * 512);
;     {
;       bf16x8 af[8];
; #pragma unroll
;       for (int i = 0; i < 8; ++i) af[i] = *(const bf16x8*)(base + a_rd + i * 2048);
; #pragma unroll
;       for (int mi = 0; mi < 8; ++mi)
; #pragma unroll
;         for (int ni = 0; ni < 4; ++ni) acc[mi][ni] = MFMA16(b0[ni], af[mi], acc[mi][ni]);
;     }
;     if (more) {
; #pragma unroll
;       for (int i = 0; i < 4; ++i) b0[i] = *(const bf16x8*)(bp + ((size_t)i * kb32 + kt * 2 + 2) * 512);
;     }
;     {
;       bf16x8 af[8];
; #pragma unroll
;       for (int i = 0; i < 8; ++i) af[i] = *(const bf16x8*)(base + ((a_rd + i * 2048) ^ 64));
; #pragma unroll
;       for (int mi = 0; mi < 8; ++mi)
; #pragma unroll
;         for (int ni = 0; ni < 4; ++ni) acc[mi][ni] = MFMA16(b1[ni], af[mi], acc[mi][ni]);
;     }
;     if (more) {
;       char* nb = smem + ((kt + 1) & 1) * 32768 + lds_w;
; #pragma unroll
;       for (int i = 0; i < 8; ++i) *(u32x4*)(nb + i * 4096) = ra[i];
.LBB0_421:
	s_add_i32 s13, s1, 0xffff8000
	s_and_b32 s13, s13, 0x8000
	s_add_i32 s13, s13, 32
	v_add_u32_e32 v0, s13, v173
	ds_read_b128 v[146:149], v0
	ds_read_b128 v[150:153], v0 offset:2048
	v_lshl_add_u64 v[154:155], v[164:165], 0, s[28:29]
	v_add_co_u32_e32 v156, vcc, s16, v154
	s_waitcnt vmcnt(3) lgkmcnt(1)
	v_mfma_f32_16x16x32_bf16 v[130:133], v[10:13], v[146:149], v[130:133]
	v_addc_co_u32_e32 v157, vcc, 0, v155, vcc
	v_add_co_u32_e32 v158, vcc, s17, v154
	s_waitcnt vmcnt(2)
	v_mfma_f32_16x16x32_bf16 v[126:129], v[14:17], v[146:149], v[126:129]
	v_addc_co_u32_e32 v159, vcc, 0, v155, vcc
	v_add_co_u32_e32 v160, vcc, s18, v154
	s_waitcnt vmcnt(1)
	v_mfma_f32_16x16x32_bf16 v[122:125], v[6:9], v[146:149], v[122:125]
	v_addc_co_u32_e32 v161, vcc, 0, v155, vcc
	v_add_co_u32_e32 v182, vcc, s24, v154
	s_waitcnt vmcnt(0)
	v_mfma_f32_16x16x32_bf16 v[118:121], v[2:5], v[146:149], v[118:121]
	v_addc_co_u32_e32 v183, vcc, 0, v155, vcc
	s_waitcnt lgkmcnt(0)
	v_mfma_f32_16x16x32_bf16 v[114:117], v[10:13], v[150:153], v[114:117]
	v_lshl_add_u64 v[164:165], v[164:165], 0, s[64:65]
	v_mfma_f32_16x16x32_bf16 v[106:109], v[14:17], v[150:153], v[106:109]
	v_mfma_f32_16x16x32_bf16 v[102:105], v[6:9], v[150:153], v[102:105]
	s_nop 0
	v_mfma_f32_16x16x32_bf16 v[98:101], v[2:5], v[150:153], v[98:101]
	ds_read_b128 v[146:149], v0 offset:4096
	ds_read_b128 v[150:153], v0 offset:6144
	s_waitcnt lgkmcnt(1)
	v_mfma_f32_16x16x32_bf16 v[94:97], v[10:13], v[146:149], v[94:97]
	v_lshl_add_u64 v[166:167], v[166:167], 0, s[60:61]
	v_mfma_f32_16x16x32_bf16 v[86:89], v[14:17], v[146:149], v[86:89]
	v_mfma_f32_16x16x32_bf16 v[82:85], v[6:9], v[146:149], v[82:85]
	s_nop 0
	v_mfma_f32_16x16x32_bf16 v[78:81], v[2:5], v[146:149], v[78:81]
	s_nop 0
	s_waitcnt lgkmcnt(0)
	v_mfma_f32_16x16x32_bf16 v[74:77], v[10:13], v[150:153], v[74:77]
	v_mfma_f32_16x16x32_bf16 v[70:73], v[14:17], v[150:153], v[70:73]
	v_mfma_f32_16x16x32_bf16 v[62:65], v[6:9], v[150:153], v[62:65]
	v_mfma_f32_16x16x32_bf16 v[66:69], v[2:5], v[150:153], v[66:69]
	ds_read_b128 v[146:149], v0 offset:8192
	ds_read_b128 v[150:153], v0 offset:10240
	s_waitcnt lgkmcnt(1)
	v_mfma_f32_16x16x32_bf16 v[46:49], v[10:13], v[146:149], v[46:49]
	v_mfma_f32_16x16x32_bf16 v[50:53], v[14:17], v[146:149], v[50:53]
	v_mfma_f32_16x16x32_bf16 v[58:61], v[6:9], v[146:149], v[58:61]
	v_mfma_f32_16x16x32_bf16 v[54:57], v[2:5], v[146:149], v[54:57]
	s_waitcnt lgkmcnt(0)
	v_mfma_f32_16x16x32_bf16 v[26:29], v[10:13], v[150:153], v[26:29]
	v_mfma_f32_16x16x32_bf16 v[22:25], v[14:17], v[150:153], v[22:25]
	v_mfma_f32_16x16x32_bf16 v[18:21], v[6:9], v[150:153], v[18:21]
	v_mfma_f32_16x16x32_bf16 v[42:45], v[2:5], v[150:153], v[42:45]
	ds_read_b128 v[146:149], v0 offset:12288
	ds_read_b128 v[150:153], v0 offset:14336
	v_add_u32_e32 v0, s13, v171
	s_and_b32 s13, s1, 0x8000
	s_waitcnt lgkmcnt(1)
	v_mfma_f32_16x16x32_bf16 v[30:33], v[10:13], v[146:149], v[30:33]
	s_add_i32 s1, s1, 0x8000
	s_cmp_eq_u32 s1, 0x80000
	v_mfma_f32_16x16x32_bf16 v[38:41], v[14:17], v[146:149], v[38:41]
	v_mfma_f32_16x16x32_bf16 v[34:37], v[6:9], v[146:149], v[34:37]
	v_mfma_f32_16x16x32_bf16 v[142:145], v[2:5], v[146:149], v[142:145]
	global_load_dwordx4 v[146:149], v[156:157], off offset:1024
	ds_read_b128 v[174:177], v0
	ds_read_b128 v[178:181], v0 offset:2048
	s_waitcnt lgkmcnt(2)
	v_mfma_f32_16x16x32_bf16 v[138:141], v[10:13], v[150:153], v[138:141]
	global_load_dwordx4 v[10:13], v[156:157], off offset:2048
	v_mfma_f32_16x16x32_bf16 v[134:137], v[14:17], v[150:153], v[134:137]
	v_mfma_f32_16x16x32_bf16 v[110:113], v[6:9], v[150:153], v[110:113]
	v_mfma_f32_16x16x32_bf16 v[90:93], v[2:5], v[150:153], v[90:93]
	global_load_dwordx4 v[150:153], v[158:159], off offset:1024
	global_load_dwordx4 v[14:17], v[158:159], off offset:2048
	global_load_dwordx4 v[154:157], v[160:161], off offset:1024
	global_load_dwordx4 v[6:9], v[160:161], off offset:2048
	s_nop 0
	global_load_dwordx4 v[158:161], v[182:183], off offset:1024
	global_load_dwordx4 v[2:5], v[182:183], off offset:2048
	v_lshrrev_b32_e32 v195, 6, v206
	v_lshl_add_u64 v[190:191], v[166:167], 0, s[28:29]
	v_lshrrev_b32_e32 v194, 3, v206
	v_readfirstlane_b32 s99, v195
	v_and_b32_e32 v194, 7, v194
	s_and_b32 s98, s1, 0x8000
	s_xor_b32 s98, s98, 0x8000
	v_lshlrev_b32_e32 v194, 4, v194
	s_lshl_b32 s99, s99, 10
	v_xor_b32_e32 v190, v194, v190
	s_add_u32 s98, s98, s99
	s_add_u32 s98, s98, 32
	s_mov_b32 s101, 0
	s_mov_b32 s100, 0x0
	v_lshl_add_u64 v[192:193], v[190:191], 0, s[100:101]
	s_mov_b32 m0, s98
	s_nop 0
	global_load_lds_dwordx4 v[192:193], off
	s_add_u32 s100, s54, 0x0
	v_lshl_add_u64 v[192:193], v[190:191], 0, s[100:101]
	s_add_u32 m0, s98, 0x1000
	s_nop 0
	global_load_lds_dwordx4 v[192:193], off
	s_add_u32 s100, s53, 0x0
	v_lshl_add_u64 v[192:193], v[190:191], 0, s[100:101]
	s_add_u32 m0, s98, 0x2000
	s_nop 0
	global_load_lds_dwordx4 v[192:193], off
	s_add_u32 s100, s52, 0x0
	v_lshl_add_u64 v[192:193], v[190:191], 0, s[100:101]
	s_add_u32 m0, s98, 0x3000
	s_nop 0
	global_load_lds_dwordx4 v[192:193], off
	s_add_u32 s100, s56, 0x0
	v_lshl_add_u64 v[192:193], v[190:191], 0, s[100:101]
	s_add_u32 m0, s98, 0x4000
	s_nop 0
	global_load_lds_dwordx4 v[192:193], off
	s_add_u32 s100, s57, 0x0
	v_lshl_add_u64 v[192:193], v[190:191], 0, s[100:101]
	s_add_u32 m0, s98, 0x5000
	s_nop 0
	global_load_lds_dwordx4 v[192:193], off
	s_add_u32 s100, s3, 0x0
	v_lshl_add_u64 v[192:193], v[190:191], 0, s[100:101]
	s_add_u32 m0, s98, 0x6000
	s_nop 0
	global_load_lds_dwordx4 v[192:193], off
	s_add_u32 s100, s19, 0x0
	v_lshl_add_u64 v[192:193], v[190:191], 0, s[100:101]
	s_add_u32 m0, s98, 0x7000
	s_nop 0
	global_load_lds_dwordx4 v[192:193], off
	s_waitcnt vmcnt(15) lgkmcnt(1)
; #define MFMA16(a, b, c) __builtin_amdgcn_mfma_f32_16x16x32_bf16((a), (b), (c), 0, 0, 0)
; template <class Epi>
; DEVI void gemm_tile256b(const bf16_t* __restrict__ A, int lda, const bf16_t* __restrict__ Bt, int K,
;                         int m0, int n0, char* smem, Epi epi) {
;     ...
;     if (more) {
; #pragma unroll
;       for (int i = 0; i < 4; ++i) b0[i] = *(const bf16x8*)(bp + ((size_t)i * kb32 + kt * 2 + 2) * 512);
;     }
;     {
;       bf16x8 af[8];
; #pragma unroll
;       for (int i = 0; i < 8; ++i) af[i] = *(const bf16x8*)(base + ((a_rd + i * 2048) ^ 64));
; #pragma unroll
;       for (int mi = 0; mi < 8; ++mi)
; #pragma unroll
;         for (int ni = 0; ni < 4; ++ni) acc[mi][ni] = MFMA16(b1[ni], af[mi], acc[mi][ni]);
;     }
	v_mfma_f32_16x16x32_bf16 v[130:133], v[146:149], v[174:177], v[130:133]
	s_waitcnt vmcnt(13)
	v_mfma_f32_16x16x32_bf16 v[126:129], v[150:153], v[174:177], v[126:129]
	s_waitcnt vmcnt(11)
	v_mfma_f32_16x16x32_bf16 v[122:125], v[154:157], v[174:177], v[122:125]
	s_waitcnt vmcnt(9)
	v_mfma_f32_16x16x32_bf16 v[118:121], v[158:161], v[174:177], v[118:121]
	s_waitcnt lgkmcnt(0)
	v_mfma_f32_16x16x32_bf16 v[114:117], v[146:149], v[178:181], v[114:117]
	v_mfma_f32_16x16x32_bf16 v[106:109], v[150:153], v[178:181], v[106:109]
	v_mfma_f32_16x16x32_bf16 v[102:105], v[154:157], v[178:181], v[102:105]
	v_mfma_f32_16x16x32_bf16 v[98:101], v[158:161], v[178:181], v[98:101]
	ds_read_b128 v[174:177], v0 offset:4096
	ds_read_b128 v[178:181], v0 offset:6144
	s_waitcnt lgkmcnt(1)
	v_mfma_f32_16x16x32_bf16 v[94:97], v[146:149], v[174:177], v[94:97]
	v_mfma_f32_16x16x32_bf16 v[86:89], v[150:153], v[174:177], v[86:89]
	v_mfma_f32_16x16x32_bf16 v[82:85], v[154:157], v[174:177], v[82:85]
	v_mfma_f32_16x16x32_bf16 v[78:81], v[158:161], v[174:177], v[78:81]
	s_waitcnt lgkmcnt(0)
	v_mfma_f32_16x16x32_bf16 v[74:77], v[146:149], v[178:181], v[74:77]
	v_mfma_f32_16x16x32_bf16 v[70:73], v[150:153], v[178:181], v[70:73]
	v_mfma_f32_16x16x32_bf16 v[62:65], v[154:157], v[178:181], v[62:65]
	v_mfma_f32_16x16x32_bf16 v[66:69], v[158:161], v[178:181], v[66:69]
	ds_read_b128 v[178:181], v0 offset:8192
	ds_read_b128 v[182:185], v0 offset:10240
	s_waitcnt lgkmcnt(1)
	v_mfma_f32_16x16x32_bf16 v[46:49], v[146:149], v[178:181], v[46:49]
	v_mfma_f32_16x16x32_bf16 v[50:53], v[150:153], v[178:181], v[50:53]
	v_mfma_f32_16x16x32_bf16 v[58:61], v[154:157], v[178:181], v[58:61]
	v_mfma_f32_16x16x32_bf16 v[54:57], v[158:161], v[178:181], v[54:57]
	s_waitcnt lgkmcnt(0)
	v_mfma_f32_16x16x32_bf16 v[26:29], v[146:149], v[182:185], v[26:29]
	v_mfma_f32_16x16x32_bf16 v[22:25], v[150:153], v[182:185], v[22:25]
	v_mfma_f32_16x16x32_bf16 v[18:21], v[154:157], v[182:185], v[18:21]
	v_mfma_f32_16x16x32_bf16 v[42:45], v[158:161], v[182:185], v[42:45]
	ds_read_b128 v[178:181], v0 offset:12288
	ds_read_b128 v[182:185], v0 offset:14336
	s_nop 0
	s_nop 0
	s_nop 0
	s_nop 0
	s_nop 0
	s_waitcnt lgkmcnt(1)
	v_mfma_f32_16x16x32_bf16 v[30:33], v[146:149], v[178:181], v[30:33]
	v_mfma_f32_16x16x32_bf16 v[38:41], v[150:153], v[178:181], v[38:41]
	v_mfma_f32_16x16x32_bf16 v[34:37], v[154:157], v[178:181], v[34:37]
	s_waitcnt vmcnt(0) lgkmcnt(0)
	s_barrier
	v_mfma_f32_16x16x32_bf16 v[142:145], v[158:161], v[178:181], v[142:145]
	v_mfma_f32_16x16x32_bf16 v[138:141], v[146:149], v[182:185], v[138:141]
	v_mfma_f32_16x16x32_bf16 v[134:137], v[150:153], v[182:185], v[134:137]
	v_mfma_f32_16x16x32_bf16 v[110:113], v[154:157], v[182:185], v[110:113]
	v_mfma_f32_16x16x32_bf16 v[90:93], v[158:161], v[182:185], v[90:93]
	s_cmp_eq_u32 s1, 0x80000
	s_cbranch_scc0 .LBB0_421
	v_add_u32_e32 v0, 32, v173
	ds_read_b128 v[146:149], v0 offset:32768
	s_movk_i32 s1, 0x7000
	s_movk_i32 s13, 0x4000
	s_waitcnt lgkmcnt(0)
	v_mfma_f32_16x16x32_bf16 v[130:133], v[10:13], v[146:149], v[130:133]
	v_mfma_f32_16x16x32_bf16 v[150:153], v[14:17], v[146:149], v[126:129]
	v_mfma_f32_16x16x32_bf16 v[154:157], v[6:9], v[146:149], v[122:125]
	v_mfma_f32_16x16x32_bf16 v[146:149], v[2:5], v[146:149], v[118:121]
	s_nop 2
	ds_read_b128 v[118:121], v0 offset:34816
	s_waitcnt lgkmcnt(0)
	v_mfma_f32_16x16x32_bf16 v[158:161], v[10:13], v[118:121], v[114:117]
	s_nop 2
	ds_read_b128 v[114:117], v0 offset:36864
	s_waitcnt lgkmcnt(0)
	v_mfma_f32_16x16x32_bf16 v[94:97], v[10:13], v[114:117], v[94:97]
	v_mfma_f32_16x16x32_bf16 v[86:89], v[14:17], v[114:117], v[86:89]
	v_mfma_f32_16x16x32_bf16 v[82:85], v[6:9], v[114:117], v[82:85]
	v_mfma_f32_16x16x32_bf16 v[78:81], v[2:5], v[114:117], v[78:81]
	ds_read_b128 v[114:117], v0 offset:38912
	s_waitcnt lgkmcnt(0)
	v_mfma_f32_16x16x32_bf16 v[74:77], v[10:13], v[114:117], v[74:77]
	v_mfma_f32_16x16x32_bf16 v[70:73], v[14:17], v[114:117], v[70:73]
	v_mfma_f32_16x16x32_bf16 v[62:65], v[6:9], v[114:117], v[62:65]
	v_mfma_f32_16x16x32_bf16 v[66:69], v[2:5], v[114:117], v[66:69]
	ds_read_b128 v[114:117], v0 offset:40960
	s_waitcnt lgkmcnt(0)
	v_mfma_f32_16x16x32_bf16 v[172:175], v[2:5], v[114:117], v[54:57]
	s_nop 2
	ds_read_b128 v[54:57], v0 offset:43008
	s_waitcnt lgkmcnt(0)
	v_mfma_f32_16x16x32_bf16 v[176:179], v[2:5], v[54:57], v[42:45]
	s_nop 2
	ds_read_b128 v[42:45], v0 offset:45056
	s_waitcnt lgkmcnt(0)
	v_mfma_f32_16x16x32_bf16 v[190:193], v[6:9], v[42:45], v[34:37]
	s_nop 2
	ds_read_b128 v[34:37], v0 offset:47104
	v_add_u32_e32 v0, 32, v171
	v_mfma_f32_16x16x32_bf16 v[106:109], v[14:17], v[118:121], v[106:109]
	v_mfma_f32_16x16x32_bf16 v[50:53], v[14:17], v[114:117], v[50:53]
	v_mfma_f32_16x16x32_bf16 v[22:25], v[14:17], v[54:57], v[22:25]
	v_mfma_f32_16x16x32_bf16 v[180:183], v[14:17], v[42:45], v[38:41]
	s_waitcnt lgkmcnt(0)
; template <class Epi>
; DEVI void gemm_tile256b(const bf16_t* __restrict__ A, int lda, const bf16_t* __restrict__ Bt, int K,
;                         int m0, int n0, char* smem, Epi epi) {
;     ...
;     for (int i = 0; i < 4; ++i) b1[i] = *(const bf16x8*)(bp + ((size_t)i * kb32 + kt * 2 + 1) * 512);
;     {
;       bf16x8 af[8];
; #pragma unroll
;       for (int i = 0; i < 8; ++i) af[i] = *(const bf16x8*)(base + a_rd + i * 2048);
; #pragma unroll
;       for (int mi = 0; mi < 8; ++mi)
; #pragma unroll
;         for (int ni = 0; ni < 4; ++ni) acc[mi][ni] = MFMA16(b0[ni], af[mi], acc[mi][ni]);
;     }
;     if (more) {
; #pragma unroll
;       for (int i = 0; i < 4; ++i) b0[i] = *(const bf16x8*)(bp + ((size_t)i * kb32 + kt * 2 + 2) * 512);
;     }
;     {
;       bf16x8 af[8];
; #pragma unroll
;       for (int i = 0; i < 8; ++i) af[i] = *(const bf16x8*)(base + ((a_rd + i * 2048) ^ 64));
; #pragma unroll
;       for (int mi = 0; mi < 8; ++mi)
; #pragma unroll
;         for (int ni = 0; ni < 4; ++ni) acc[mi][ni] = MFMA16(b1[ni], af[mi], acc[mi][ni]);
;     }
;     if (more) {
;       char* nb = smem + ((kt + 1) & 1) * 32768 + lds_w;
; #pragma unroll
;       for (int i = 0; i < 8; ++i) *(u32x4*)(nb + i * 4096) = ra[i];
;     }
;     __syncthreads();
;   }
; #pragma unroll
;   for (int mi = 0; mi < 8; ++mi)
; #pragma unroll
;     for (int ni = 0; ni < 4; ++ni)
;       epi(m0 + wm * 128 + mi * 16 + l15, n0 + wn * 64 + ni * 16 + quad * 4, acc[mi][ni]);
;   DEVI void operator()(int m, int n, f32x4 v) const {
;     if (n < 1024) {
;       if (m >= L) return;
;       const bool isq = n < 512;
;       const int nn = n & 511;
;       const int h = nn >> 7, c = (nn >> 6) & 1, d = nn & 63;
;       const float s = isq ? (0.125f * LOG2E) : 1.0f;
;       bf16_t* dst = isq ? r0 + R0_Q + ((size_t)(h * 2 + c) * LR + m) * 64 + d
;                         : r0 + R0_K + (size_t)(h * 2 + c) * LR * 64 + wfm(m, d, 64);
;       *(u32x2*)dst = u32x2{pack2(v[0] * s, v[1] * s), pack2(v[2] * s, v[3] * s)};
;     } else if (n < 1536) {
;       const int nn = n - 1024;
;       bf16_t* dst = r0 + R0_VT + (size_t)nn * LR + m;
;       const bool ok = m < L;
; #pragma unroll
;       for (int i = 0; i < 4; ++i) {
;         dst[(size_t)i * LR] = ok ? f2bf(v[i]) : (bf16_t)0;
;         if (m >= 16384) {
;           dst[(size_t)i * LR + 16] = 0;
;           dst[(size_t)i * LR + 32] = 0;
	v_mfma_f32_16x16x32_bf16 v[134:137], v[14:17], v[34:37], v[134:137]
	v_add_co_u32_e32 v14, vcc, s1, v162
	s_mov_b32 s1, 0xf000
	s_nop 0
	v_addc_co_u32_e32 v15, vcc, 0, v163, vcc
	v_add_co_u32_e32 v38, vcc, s1, v162
	v_mfma_f32_16x16x32_bf16 v[46:49], v[10:13], v[114:117], v[46:49]
	s_nop 0
	v_addc_co_u32_e32 v39, vcc, 0, v163, vcc
	global_load_dwordx4 v[14:17], v[14:15], off offset:3072
	v_mfma_f32_16x16x32_bf16 v[26:29], v[10:13], v[54:57], v[26:29]
	s_mov_b32 s1, 0x17000
	v_mfma_f32_16x16x32_bf16 v[30:33], v[10:13], v[42:45], v[30:33]
	v_mfma_f32_16x16x32_bf16 v[10:13], v[10:13], v[34:37], v[138:141]
	s_nop 2
	global_load_dwordx4 v[138:141], v[38:39], off offset:3072
	v_mfma_f32_16x16x32_bf16 v[102:105], v[6:9], v[118:121], v[102:105]
	v_add_co_u32_e32 v38, vcc, s1, v162
	s_mov_b32 s1, 0x1f000
	v_mfma_f32_16x16x32_bf16 v[98:101], v[2:5], v[118:121], v[98:101]
	v_addc_co_u32_e32 v39, vcc, 0, v163, vcc
	global_load_dwordx4 v[198:201], v[38:39], off offset:3072
	v_mfma_f32_16x16x32_bf16 v[164:167], v[6:9], v[114:117], v[58:61]
	v_add_co_u32_e32 v38, vcc, s1, v162
	v_mfma_f32_16x16x32_bf16 v[18:21], v[6:9], v[54:57], v[18:21]
	s_nop 0
	v_addc_co_u32_e32 v39, vcc, 0, v163, vcc
	v_mfma_f32_16x16x32_bf16 v[194:197], v[2:5], v[42:45], v[142:145]
	v_mfma_f32_16x16x32_bf16 v[6:9], v[6:9], v[34:37], v[110:113]
	s_nop 1
	v_and_b32_e32 v142, 15, v170
	v_lshlrev_b32_e32 v143, 2, v169
	v_mfma_f32_16x16x32_bf16 v[2:5], v[2:5], v[34:37], v[90:93]
	ds_read_b128 v[34:37], v0 offset:32768
	s_waitcnt vmcnt(1) lgkmcnt(0)
	v_mfma_f32_16x16x32_bf16 v[122:125], v[138:141], v[34:37], v[150:153]
	s_nop 2
	global_load_dwordx4 v[150:153], v[38:39], off offset:3072
	v_mfma_f32_16x16x32_bf16 v[126:129], v[14:17], v[34:37], v[130:133]
	s_waitcnt vmcnt(1)
	v_mfma_f32_16x16x32_bf16 v[118:121], v[198:201], v[34:37], v[154:157]
	s_nop 0
	v_or_b32_e32 v130, v143, v168
	s_waitcnt vmcnt(0)
	v_mfma_f32_16x16x32_bf16 v[114:117], v[150:153], v[34:37], v[146:149]
	ds_read_b128 v[34:37], v0 offset:34816
	s_nop 1
	ds_read_b128 v[144:147], v0 offset:47104
	s_waitcnt lgkmcnt(1)
	v_mfma_f32_16x16x32_bf16 v[110:113], v[14:17], v[34:37], v[158:161]
	v_mfma_f32_16x16x32_bf16 v[106:109], v[138:141], v[34:37], v[106:109]
	v_mfma_f32_16x16x32_bf16 v[102:105], v[198:201], v[34:37], v[102:105]
	v_mfma_f32_16x16x32_bf16 v[98:101], v[150:153], v[34:37], v[98:101]
	ds_read_b128 v[34:37], v0 offset:36864
	s_waitcnt lgkmcnt(0)
	v_mfma_f32_16x16x32_bf16 v[94:97], v[14:17], v[34:37], v[94:97]
	v_mfma_f32_16x16x32_bf16 v[90:93], v[138:141], v[34:37], v[86:89]
	v_mfma_f32_16x16x32_bf16 v[86:89], v[198:201], v[34:37], v[82:85]
	v_mfma_f32_16x16x32_bf16 v[82:85], v[150:153], v[34:37], v[78:81]
	ds_read_b128 v[34:37], v0 offset:38912
	s_waitcnt lgkmcnt(0)
	v_mfma_f32_16x16x32_bf16 v[78:81], v[14:17], v[34:37], v[74:77]
	v_mfma_f32_16x16x32_bf16 v[74:77], v[138:141], v[34:37], v[70:73]
	v_mfma_f32_16x16x32_bf16 v[70:73], v[198:201], v[34:37], v[62:65]
	v_mfma_f32_16x16x32_bf16 v[66:69], v[150:153], v[34:37], v[66:69]
	ds_read_b128 v[34:37], v0 offset:40960
	s_waitcnt lgkmcnt(0)
	v_mfma_f32_16x16x32_bf16 v[62:65], v[14:17], v[34:37], v[46:49]
	v_mfma_f32_16x16x32_bf16 v[58:61], v[138:141], v[34:37], v[50:53]
	v_mfma_f32_16x16x32_bf16 v[54:57], v[198:201], v[34:37], v[164:167]
	v_mfma_f32_16x16x32_bf16 v[50:53], v[150:153], v[34:37], v[172:175]
	ds_read_b128 v[34:37], v0 offset:43008
	s_waitcnt lgkmcnt(0)
	v_mfma_f32_16x16x32_bf16 v[38:41], v[198:201], v[34:37], v[18:21]
	s_nop 2
	ds_read_b128 v[18:21], v0 offset:45056
	v_and_b32_e32 v0, 0xffffff80, v170
	v_add_u32_e32 v0, s0, v0
	v_mfma_f32_16x16x32_bf16 v[46:49], v[14:17], v[34:37], v[26:29]
	v_or_b32_e32 v132, v0, v142
	v_ashrrev_i32_e32 v133, 31, v132
	s_movk_i32 s0, 0x4010
	v_mfma_f32_16x16x32_bf16 v[42:45], v[138:141], v[34:37], v[22:25]
	v_cmp_gt_i32_e64 s[46:47], s13, v132
	s_movk_i32 s13, 0x3ff
	v_cmp_gt_i32_e64 s[0:1], s0, v132
	v_mfma_f32_16x16x32_bf16 v[34:37], v[150:153], v[34:37], v[176:179]
	v_cmp_lt_i32_e64 s[42:43], s13, v130
	s_waitcnt lgkmcnt(0)
	s_barrier
	v_mfma_f32_16x16x32_bf16 v[30:33], v[14:17], v[18:21], v[30:33]
	v_mfma_f32_16x16x32_bf16 v[26:29], v[138:141], v[18:21], v[180:183]
	v_mfma_f32_16x16x32_bf16 v[22:25], v[198:201], v[18:21], v[190:193]
	v_mfma_f32_16x16x32_bf16 v[18:21], v[150:153], v[18:21], v[194:197]
	v_mfma_f32_16x16x32_bf16 v[14:17], v[14:17], v[144:147], v[10:13]
	v_mfma_f32_16x16x32_bf16 v[10:13], v[138:141], v[144:147], v[134:137]
	v_mfma_f32_16x16x32_bf16 v[6:9], v[198:201], v[144:147], v[6:9]
	s_nop 1
	v_lshlrev_b64 v[134:135], 10, v[132:133]
	v_lshl_add_u64 v[136:137], s[30:31], 0, v[134:135]
	v_lshl_add_u64 v[134:135], v[132:133], 1, s[6:7]
	v_mfma_f32_16x16x32_bf16 v[2:5], v[150:153], v[144:147], v[2:5]
	s_and_saveexec_b64 s[16:17], s[42:43]
	s_xor_b64 s[16:17], exec, s[16:17]
	s_cbranch_execz .LBB0_437
	s_cmpk_gt_u32 s62, 0x5ff
	s_mov_b64 s[36:37], -1
	s_cbranch_scc0 .LBB0_427
	s_and_saveexec_b64 s[36:37], s[0:1]
	s_cbranch_execz .LBB0_426
	v_mov_b32_e32 v131, v1
	v_lshl_add_u64 v[138:139], v[130:131], 1, v[136:137]
	v_add_co_u32_e32 v138, vcc, 0x305f000, v138
	v_cvt_pk_bf16_f32 v140, v126, v127
	v_cvt_pk_bf16_f32 v141, v128, v129
	v_addc_co_u32_e32 v139, vcc, 0, v139, vcc
	global_store_dwordx2 v[138:139], v[140:141], off offset:1024

; #define MFMA16(a, b, c) __builtin_amdgcn_mfma_f32_16x16x32_bf16((a), (b), (c), 0, 0, 0)
; template <class Epi>
; DEVI void gemm_tile256b(const bf16_t* __restrict__ A, int lda, const bf16_t* __restrict__ Bt, int K,
;                         int m0, int n0, char* smem, Epi epi) {
;     ...
;   for (int kt = 0; kt < nk; ++kt) {
;     const char* base = smem + (kt & 1) * 32768;
;     const bool more = kt + 1 < nk;
;     if (more) {
; #pragma unroll
;       for (int i = 0; i < 8; ++i) ra[i] = *(const u32x4*)(ag + (size_t)(i * 32) * lda + (kt + 1) * 64);
;     }
; #pragma unroll
;     for (int i = 0; i < 4; ++i) b1[i] = *(const bf16x8*)(bp + ((size_t)i * kb32 + kt * 2 + 1) * 512);
;     {
;       bf16x8 af[8];
; #pragma unroll
;       for (int i = 0; i < 8; ++i) af[i] = *(const bf16x8*)(base + a_rd + i * 2048);
; #pragma unroll
;       for (int mi = 0; mi < 8; ++mi)
; #pragma unroll
;         for (int ni = 0; ni < 4; ++ni) acc[mi][ni] = MFMA16(b0[ni], af[mi], acc[mi][ni]);
;     }
;     if (more) {
; #pragma unroll
;       for (int i = 0; i < 4; ++i) b0[i] = *(const bf16x8*)(bp + ((size_t)i * kb32 + kt * 2 + 2) * 512);
;     }
;     {
;       bf16x8 af[8];
; #pragma unroll
;       for (int i = 0; i < 8; ++i) af[i] = *(const bf16x8*)(base + ((a_rd + i * 2048) ^ 64));
; #pragma unroll
;       for (int mi = 0; mi < 8; ++mi)
; #pragma unroll
;         for (int ni = 0; ni < 4; ++ni) acc[mi][ni] = MFMA16(b1[ni], af[mi], acc[mi][ni]);
;     }
;     if (more) {
;       char* nb = smem + ((kt + 1) & 1) * 32768 + lds_w;
; #pragma unroll
;       for (int i = 0; i < 8; ++i) *(u32x4*)(nb + i * 4096) = ra[i];
;     }
;     __syncthreads();
;   }
.LBB0_1367:
	s_add_i32 s10, s1, 0xffff8000
	s_and_b32 s10, s10, 0x8000
	s_add_i32 s10, s10, 32
	v_add_u32_e32 v0, s10, v173
	ds_read_b128 v[146:149], v0
	ds_read_b128 v[150:153], v0 offset:2048
	v_lshl_add_u64 v[154:155], v[164:165], 0, s[28:29]
	v_add_co_u32_e32 v156, vcc, s11, v154
	s_waitcnt vmcnt(3) lgkmcnt(1)
	v_mfma_f32_16x16x32_bf16 v[130:133], v[2:5], v[146:149], v[130:133]
	v_addc_co_u32_e32 v157, vcc, 0, v155, vcc
	v_add_co_u32_e32 v158, vcc, s13, v154
	s_waitcnt vmcnt(2)
	v_mfma_f32_16x16x32_bf16 v[126:129], v[14:17], v[146:149], v[126:129]
	v_addc_co_u32_e32 v159, vcc, 0, v155, vcc
	v_add_co_u32_e32 v160, vcc, s16, v154
	s_waitcnt vmcnt(1)
	v_mfma_f32_16x16x32_bf16 v[122:125], v[10:13], v[146:149], v[122:125]
	v_addc_co_u32_e32 v161, vcc, 0, v155, vcc
	v_add_co_u32_e32 v182, vcc, s17, v154
	s_waitcnt vmcnt(0)
	v_mfma_f32_16x16x32_bf16 v[118:121], v[6:9], v[146:149], v[118:121]
	v_addc_co_u32_e32 v183, vcc, 0, v155, vcc
	s_waitcnt lgkmcnt(0)
	v_mfma_f32_16x16x32_bf16 v[114:117], v[2:5], v[150:153], v[114:117]
	v_lshl_add_u64 v[164:165], v[164:165], 0, s[64:65]
	v_mfma_f32_16x16x32_bf16 v[106:109], v[14:17], v[150:153], v[106:109]
	v_mfma_f32_16x16x32_bf16 v[102:105], v[10:13], v[150:153], v[102:105]
	s_nop 0
	v_mfma_f32_16x16x32_bf16 v[98:101], v[6:9], v[150:153], v[98:101]
	ds_read_b128 v[146:149], v0 offset:4096
	ds_read_b128 v[150:153], v0 offset:6144
	s_waitcnt lgkmcnt(1)
	v_mfma_f32_16x16x32_bf16 v[94:97], v[2:5], v[146:149], v[94:97]
	v_lshl_add_u64 v[166:167], v[166:167], 0, s[60:61]
	v_mfma_f32_16x16x32_bf16 v[86:89], v[14:17], v[146:149], v[86:89]
	v_mfma_f32_16x16x32_bf16 v[82:85], v[10:13], v[146:149], v[82:85]
	s_nop 0
	v_mfma_f32_16x16x32_bf16 v[78:81], v[6:9], v[146:149], v[78:81]
	s_nop 0
	s_waitcnt lgkmcnt(0)
	v_mfma_f32_16x16x32_bf16 v[74:77], v[2:5], v[150:153], v[74:77]
	v_mfma_f32_16x16x32_bf16 v[70:73], v[14:17], v[150:153], v[70:73]
	v_mfma_f32_16x16x32_bf16 v[62:65], v[10:13], v[150:153], v[62:65]
	v_mfma_f32_16x16x32_bf16 v[66:69], v[6:9], v[150:153], v[66:69]
	ds_read_b128 v[146:149], v0 offset:8192
	ds_read_b128 v[150:153], v0 offset:10240
	s_waitcnt lgkmcnt(1)
	v_mfma_f32_16x16x32_bf16 v[46:49], v[2:5], v[146:149], v[46:49]
	v_mfma_f32_16x16x32_bf16 v[50:53], v[14:17], v[146:149], v[50:53]
	v_mfma_f32_16x16x32_bf16 v[58:61], v[10:13], v[146:149], v[58:61]
	v_mfma_f32_16x16x32_bf16 v[54:57], v[6:9], v[146:149], v[54:57]
	s_waitcnt lgkmcnt(0)
	v_mfma_f32_16x16x32_bf16 v[26:29], v[2:5], v[150:153], v[26:29]
	v_mfma_f32_16x16x32_bf16 v[22:25], v[14:17], v[150:153], v[22:25]
	v_mfma_f32_16x16x32_bf16 v[18:21], v[10:13], v[150:153], v[18:21]
	v_mfma_f32_16x16x32_bf16 v[42:45], v[6:9], v[150:153], v[42:45]
	ds_read_b128 v[146:149], v0 offset:12288
	ds_read_b128 v[150:153], v0 offset:14336
	v_add_u32_e32 v0, s10, v171
	s_and_b32 s10, s1, 0x8000
	s_waitcnt lgkmcnt(1)
	v_mfma_f32_16x16x32_bf16 v[30:33], v[2:5], v[146:149], v[30:33]
	s_add_i32 s1, s1, 0x8000
	s_cmp_eq_u32 s1, 0x80000
	v_mfma_f32_16x16x32_bf16 v[38:41], v[14:17], v[146:149], v[38:41]
	v_mfma_f32_16x16x32_bf16 v[34:37], v[10:13], v[146:149], v[34:37]
	v_mfma_f32_16x16x32_bf16 v[142:145], v[6:9], v[146:149], v[142:145]
	global_load_dwordx4 v[146:149], v[156:157], off offset:1024
	ds_read_b128 v[174:177], v0
	ds_read_b128 v[178:181], v0 offset:2048
	s_waitcnt lgkmcnt(2)
	v_mfma_f32_16x16x32_bf16 v[138:141], v[2:5], v[150:153], v[138:141]
	global_load_dwordx4 v[2:5], v[156:157], off offset:2048
	v_mfma_f32_16x16x32_bf16 v[134:137], v[14:17], v[150:153], v[134:137]
	v_mfma_f32_16x16x32_bf16 v[110:113], v[10:13], v[150:153], v[110:113]
	v_mfma_f32_16x16x32_bf16 v[90:93], v[6:9], v[150:153], v[90:93]
	global_load_dwordx4 v[150:153], v[158:159], off offset:1024
	global_load_dwordx4 v[14:17], v[158:159], off offset:2048
	global_load_dwordx4 v[154:157], v[160:161], off offset:1024
	global_load_dwordx4 v[10:13], v[160:161], off offset:2048
	s_nop 0
	global_load_dwordx4 v[158:161], v[182:183], off offset:1024
	global_load_dwordx4 v[6:9], v[182:183], off offset:2048
	v_lshrrev_b32_e32 v195, 6, v206
	v_lshl_add_u64 v[190:191], v[166:167], 0, s[28:29]
	v_lshrrev_b32_e32 v194, 3, v206
	v_readfirstlane_b32 s99, v195
	v_and_b32_e32 v194, 7, v194
	s_and_b32 s98, s1, 0x8000
	s_xor_b32 s98, s98, 0x8000
	v_lshlrev_b32_e32 v194, 4, v194
	s_lshl_b32 s99, s99, 10
	v_xor_b32_e32 v190, v194, v190
	s_add_u32 s98, s98, s99
	s_add_u32 s98, s98, 32
	s_mov_b32 s101, 0
	s_mov_b32 s100, 0x0
	v_lshl_add_u64 v[192:193], v[190:191], 0, s[100:101]
	s_mov_b32 m0, s98
	s_nop 0
	global_load_lds_dwordx4 v[192:193], off
	s_add_u32 s100, s54, 0x0
	v_lshl_add_u64 v[192:193], v[190:191], 0, s[100:101]
	s_add_u32 m0, s98, 0x1000
	s_nop 0
	global_load_lds_dwordx4 v[192:193], off
	s_add_u32 s100, s53, 0x0
	v_lshl_add_u64 v[192:193], v[190:191], 0, s[100:101]
	s_add_u32 m0, s98, 0x2000
	s_nop 0
	global_load_lds_dwordx4 v[192:193], off
	s_add_u32 s100, s52, 0x0
	v_lshl_add_u64 v[192:193], v[190:191], 0, s[100:101]
	s_add_u32 m0, s98, 0x3000
	s_nop 0
	global_load_lds_dwordx4 v[192:193], off
	s_add_u32 s100, s56, 0x0
	v_lshl_add_u64 v[192:193], v[190:191], 0, s[100:101]
	s_add_u32 m0, s98, 0x4000
	s_nop 0
	global_load_lds_dwordx4 v[192:193], off
	s_add_u32 s100, s57, 0x0
	v_lshl_add_u64 v[192:193], v[190:191], 0, s[100:101]
	s_add_u32 m0, s98, 0x5000
	s_nop 0
	global_load_lds_dwordx4 v[192:193], off
	s_add_u32 s100, s3, 0x0
	v_lshl_add_u64 v[192:193], v[190:191], 0, s[100:101]
	s_add_u32 m0, s98, 0x6000
	s_nop 0
	global_load_lds_dwordx4 v[192:193], off
	s_add_u32 s100, s19, 0x0
	v_lshl_add_u64 v[192:193], v[190:191], 0, s[100:101]
	s_add_u32 m0, s98, 0x7000
	s_nop 0
	global_load_lds_dwordx4 v[192:193], off
	s_waitcnt vmcnt(15) lgkmcnt(1)
; #define MFMA16(a, b, c) __builtin_amdgcn_mfma_f32_16x16x32_bf16((a), (b), (c), 0, 0, 0)
; template <class Epi>
; DEVI void gemm_tile256b(const bf16_t* __restrict__ A, int lda, const bf16_t* __restrict__ Bt, int K,
;                         int m0, int n0, char* smem, Epi epi) {
;     ...
;   for (int kt = 0; kt < nk; ++kt) {
;     const char* base = smem + (kt & 1) * 32768;
;     const bool more = kt + 1 < nk;
;     if (more) {
; #pragma unroll
;       for (int i = 0; i < 8; ++i) ra[i] = *(const u32x4*)(ag + (size_t)(i * 32) * lda + (kt + 1) * 64);
;     }
; #pragma unroll
;     for (int i = 0; i < 4; ++i) b1[i] = *(const bf16x8*)(bp + ((size_t)i * kb32 + kt * 2 + 1) * 512);
;     {
;       bf16x8 af[8];
; #pragma unroll
;       for (int i = 0; i < 8; ++i) af[i] = *(const bf16x8*)(base + a_rd + i * 2048);
; #pragma unroll
;       for (int mi = 0; mi < 8; ++mi)
; #pragma unroll
;         for (int ni = 0; ni < 4; ++ni) acc[mi][ni] = MFMA16(b0[ni], af[mi], acc[mi][ni]);
;     }
;     if (more) {
; #pragma unroll
;       for (int i = 0; i < 4; ++i) b0[i] = *(const bf16x8*)(bp + ((size_t)i * kb32 + kt * 2 + 2) * 512);
;     }
;     {
;       bf16x8 af[8];
; #pragma unroll
;       for (int i = 0; i < 8; ++i) af[i] = *(const bf16x8*)(base + ((a_rd + i * 2048) ^ 64));
; #pragma unroll
;       for (int mi = 0; mi < 8; ++mi)
; #pragma unroll
;         for (int ni = 0; ni < 4; ++ni) acc[mi][ni] = MFMA16(b1[ni], af[mi], acc[mi][ni]);
;     }
;     if (more) {
;       char* nb = smem + ((kt + 1) & 1) * 32768 + lds_w;
; #pragma unroll
;       for (int i = 0; i < 8; ++i) *(u32x4*)(nb + i * 4096) = ra[i];
;     }
;     __syncthreads();
;   }
	v_mfma_f32_16x16x32_bf16 v[130:133], v[146:149], v[174:177], v[130:133]
	s_waitcnt vmcnt(13)
	v_mfma_f32_16x16x32_bf16 v[126:129], v[150:153], v[174:177], v[126:129]
	s_waitcnt vmcnt(11)
	v_mfma_f32_16x16x32_bf16 v[122:125], v[154:157], v[174:177], v[122:125]
	s_waitcnt vmcnt(9)
	v_mfma_f32_16x16x32_bf16 v[118:121], v[158:161], v[174:177], v[118:121]
	s_waitcnt lgkmcnt(0)
	v_mfma_f32_16x16x32_bf16 v[114:117], v[146:149], v[178:181], v[114:117]
	v_mfma_f32_16x16x32_bf16 v[106:109], v[150:153], v[178:181], v[106:109]
	v_mfma_f32_16x16x32_bf16 v[102:105], v[154:157], v[178:181], v[102:105]
	v_mfma_f32_16x16x32_bf16 v[98:101], v[158:161], v[178:181], v[98:101]
	ds_read_b128 v[174:177], v0 offset:4096
	ds_read_b128 v[178:181], v0 offset:6144
	s_waitcnt lgkmcnt(1)
	v_mfma_f32_16x16x32_bf16 v[94:97], v[146:149], v[174:177], v[94:97]
	v_mfma_f32_16x16x32_bf16 v[86:89], v[150:153], v[174:177], v[86:89]
	v_mfma_f32_16x16x32_bf16 v[82:85], v[154:157], v[174:177], v[82:85]
	v_mfma_f32_16x16x32_bf16 v[78:81], v[158:161], v[174:177], v[78:81]
	s_waitcnt lgkmcnt(0)
	v_mfma_f32_16x16x32_bf16 v[74:77], v[146:149], v[178:181], v[74:77]
	v_mfma_f32_16x16x32_bf16 v[70:73], v[150:153], v[178:181], v[70:73]
	v_mfma_f32_16x16x32_bf16 v[62:65], v[154:157], v[178:181], v[62:65]
	v_mfma_f32_16x16x32_bf16 v[66:69], v[158:161], v[178:181], v[66:69]
	ds_read_b128 v[178:181], v0 offset:8192
	ds_read_b128 v[182:185], v0 offset:10240
	s_waitcnt lgkmcnt(1)
	v_mfma_f32_16x16x32_bf16 v[46:49], v[146:149], v[178:181], v[46:49]
	v_mfma_f32_16x16x32_bf16 v[50:53], v[150:153], v[178:181], v[50:53]
	v_mfma_f32_16x16x32_bf16 v[58:61], v[154:157], v[178:181], v[58:61]
	v_mfma_f32_16x16x32_bf16 v[54:57], v[158:161], v[178:181], v[54:57]
	s_waitcnt lgkmcnt(0)
	v_mfma_f32_16x16x32_bf16 v[26:29], v[146:149], v[182:185], v[26:29]
	v_mfma_f32_16x16x32_bf16 v[22:25], v[150:153], v[182:185], v[22:25]
	v_mfma_f32_16x16x32_bf16 v[18:21], v[154:157], v[182:185], v[18:21]
	v_mfma_f32_16x16x32_bf16 v[42:45], v[158:161], v[182:185], v[42:45]
	ds_read_b128 v[178:181], v0 offset:12288
	ds_read_b128 v[182:185], v0 offset:14336
	s_nop 0
	s_nop 0
	s_nop 0
	s_nop 0
	s_nop 0
	s_waitcnt lgkmcnt(1)
	v_mfma_f32_16x16x32_bf16 v[30:33], v[146:149], v[178:181], v[30:33]
	v_mfma_f32_16x16x32_bf16 v[38:41], v[150:153], v[178:181], v[38:41]
	v_mfma_f32_16x16x32_bf16 v[34:37], v[154:157], v[178:181], v[34:37]
	s_waitcnt vmcnt(0) lgkmcnt(0)
	s_barrier
	v_mfma_f32_16x16x32_bf16 v[142:145], v[158:161], v[178:181], v[142:145]
	v_mfma_f32_16x16x32_bf16 v[138:141], v[146:149], v[182:185], v[138:141]
	v_mfma_f32_16x16x32_bf16 v[134:137], v[150:153], v[182:185], v[134:137]
	v_mfma_f32_16x16x32_bf16 v[110:113], v[154:157], v[182:185], v[110:113]
	v_mfma_f32_16x16x32_bf16 v[90:93], v[158:161], v[182:185], v[90:93]
	s_cmp_eq_u32 s1, 0x80000
	s_cbranch_scc0 .LBB0_1367
	v_add_u32_e32 v0, 32, v173
	ds_read_b128 v[146:149], v0 offset:32768
	s_movk_i32 s1, 0x7000
	s_movk_i32 s10, 0x1800
	s_waitcnt lgkmcnt(0)
	v_mfma_f32_16x16x32_bf16 v[130:133], v[2:5], v[146:149], v[130:133]
	v_mfma_f32_16x16x32_bf16 v[150:153], v[14:17], v[146:149], v[126:129]
	v_mfma_f32_16x16x32_bf16 v[154:157], v[10:13], v[146:149], v[122:125]
	v_mfma_f32_16x16x32_bf16 v[146:149], v[6:9], v[146:149], v[118:121]
	s_nop 2
	ds_read_b128 v[118:121], v0 offset:34816
	s_waitcnt lgkmcnt(0)
	v_mfma_f32_16x16x32_bf16 v[158:161], v[2:5], v[118:121], v[114:117]
	s_nop 2
	ds_read_b128 v[114:117], v0 offset:36864
	s_waitcnt lgkmcnt(0)
	v_mfma_f32_16x16x32_bf16 v[94:97], v[2:5], v[114:117], v[94:97]
	v_mfma_f32_16x16x32_bf16 v[86:89], v[14:17], v[114:117], v[86:89]
	v_mfma_f32_16x16x32_bf16 v[82:85], v[10:13], v[114:117], v[82:85]
	v_mfma_f32_16x16x32_bf16 v[78:81], v[6:9], v[114:117], v[78:81]
	ds_read_b128 v[114:117], v0 offset:38912
	s_waitcnt lgkmcnt(0)
	v_mfma_f32_16x16x32_bf16 v[74:77], v[2:5], v[114:117], v[74:77]
	v_mfma_f32_16x16x32_bf16 v[70:73], v[14:17], v[114:117], v[70:73]
	v_mfma_f32_16x16x32_bf16 v[62:65], v[10:13], v[114:117], v[62:65]
	v_mfma_f32_16x16x32_bf16 v[66:69], v[6:9], v[114:117], v[66:69]
	ds_read_b128 v[114:117], v0 offset:40960
	s_waitcnt lgkmcnt(0)
	v_mfma_f32_16x16x32_bf16 v[172:175], v[6:9], v[114:117], v[54:57]
	s_nop 2
	ds_read_b128 v[54:57], v0 offset:43008
	s_waitcnt lgkmcnt(0)
	v_mfma_f32_16x16x32_bf16 v[176:179], v[6:9], v[54:57], v[42:45]
	s_nop 2
	ds_read_b128 v[42:45], v0 offset:45056
	s_waitcnt lgkmcnt(0)
	v_mfma_f32_16x16x32_bf16 v[190:193], v[10:13], v[42:45], v[34:37]
	s_nop 2
	ds_read_b128 v[34:37], v0 offset:47104
	v_add_u32_e32 v0, 32, v171
	v_mfma_f32_16x16x32_bf16 v[106:109], v[14:17], v[118:121], v[106:109]
	v_mfma_f32_16x16x32_bf16 v[50:53], v[14:17], v[114:117], v[50:53]
	v_mfma_f32_16x16x32_bf16 v[22:25], v[14:17], v[54:57], v[22:25]
	v_mfma_f32_16x16x32_bf16 v[180:183], v[14:17], v[42:45], v[38:41]
	s_waitcnt lgkmcnt(0)
; #define MFMA16(a, b, c) __builtin_amdgcn_mfma_f32_16x16x32_bf16((a), (b), (c), 0, 0, 0)
; template <class Epi>
; DEVI void gemm_tile256b(const bf16_t* __restrict__ A, int lda, const bf16_t* __restrict__ Bt, int K,
;                         int m0, int n0, char* smem, Epi epi) {
;     ...
;     for (int i = 0; i < 4; ++i) b1[i] = *(const bf16x8*)(bp + ((size_t)i * kb32 + kt * 2 + 1) * 512);
;     {
;       bf16x8 af[8];
; #pragma unroll
;       for (int i = 0; i < 8; ++i) af[i] = *(const bf16x8*)(base + a_rd + i * 2048);
; #pragma unroll
;       for (int mi = 0; mi < 8; ++mi)
; #pragma unroll
;         for (int ni = 0; ni < 4; ++ni) acc[mi][ni] = MFMA16(b0[ni], af[mi], acc[mi][ni]);
;     }
;     if (more) {
; #pragma unroll
;       for (int i = 0; i < 4; ++i) b0[i] = *(const bf16x8*)(bp + ((size_t)i * kb32 + kt * 2 + 2) * 512);
;     }
;     {
;       bf16x8 af[8];
; #pragma unroll
;       for (int i = 0; i < 8; ++i) af[i] = *(const bf16x8*)(base + ((a_rd + i * 2048) ^ 64));
; #pragma unroll
;       for (int mi = 0; mi < 8; ++mi)
; #pragma unroll
;         for (int ni = 0; ni < 4; ++ni) acc[mi][ni] = MFMA16(b1[ni], af[mi], acc[mi][ni]);
;     }
;     if (more) {
;       char* nb = smem + ((kt + 1) & 1) * 32768 + lds_w;
; #pragma unroll
;       for (int i = 0; i < 8; ++i) *(u32x4*)(nb + i * 4096) = ra[i];
;     }
;     __syncthreads();
;   }
; #pragma unroll
;   for (int mi = 0; mi < 8; ++mi)
; #pragma unroll
;     for (int ni = 0; ni < 4; ++ni)
;       epi(m0 + wm * 128 + mi * 16 + l15, n0 + wn * 64 + ni * 16 + quad * 4, acc[mi][ni]);
;   DEVI void operator()(int m, int n, f32x4 v) const {
;     if (m >= L) return;
;     if (n < 3072) {
;       *(u32x2*)(raw + (size_t)m * 3072 + n) = u32x2{pack2(v[0], v[1]), pack2(v[2], v[3])};
;     } else if (n < 3088) {
;       *(f32x4*)(ba + (size_t)m * 16 + (n - 3072)) = v;
;     }
	v_mfma_f32_16x16x32_bf16 v[134:137], v[14:17], v[34:37], v[134:137]
	v_add_co_u32_e32 v14, vcc, s1, v162
	s_mov_b32 s1, 0xf000
	s_nop 0
	v_addc_co_u32_e32 v15, vcc, 0, v163, vcc
	v_mfma_f32_16x16x32_bf16 v[102:105], v[10:13], v[118:121], v[102:105]
	global_load_dwordx4 v[14:17], v[14:15], off offset:3072
	v_mfma_f32_16x16x32_bf16 v[46:49], v[2:5], v[114:117], v[46:49]
	v_mfma_f32_16x16x32_bf16 v[164:167], v[10:13], v[114:117], v[58:61]
	v_mfma_f32_16x16x32_bf16 v[26:29], v[2:5], v[54:57], v[26:29]
	v_mfma_f32_16x16x32_bf16 v[18:21], v[10:13], v[54:57], v[18:21]
	v_mfma_f32_16x16x32_bf16 v[30:33], v[2:5], v[42:45], v[30:33]
	v_mfma_f32_16x16x32_bf16 v[2:5], v[2:5], v[34:37], v[138:141]
	v_mfma_f32_16x16x32_bf16 v[138:141], v[10:13], v[34:37], v[110:113]
	v_add_co_u32_e32 v10, vcc, s1, v162
	s_mov_b32 s1, 0x17000
	s_nop 0
	v_addc_co_u32_e32 v11, vcc, 0, v163, vcc
	global_load_dwordx4 v[10:13], v[10:11], off offset:3072
	v_mfma_f32_16x16x32_bf16 v[98:101], v[6:9], v[118:121], v[98:101]
	v_mfma_f32_16x16x32_bf16 v[142:145], v[6:9], v[42:45], v[142:145]
	v_mfma_f32_16x16x32_bf16 v[194:197], v[6:9], v[34:37], v[90:93]
	ds_read_b128 v[6:9], v0 offset:32768
	v_add_co_u32_e32 v34, vcc, s1, v162
	s_mov_b32 s1, 0x1f000
	s_nop 0
	v_addc_co_u32_e32 v35, vcc, 0, v163, vcc
	global_load_dwordx4 v[198:201], v[34:35], off offset:3072
	v_add_co_u32_e32 v34, vcc, s1, v162
	s_waitcnt vmcnt(1) lgkmcnt(0)
	v_mfma_f32_16x16x32_bf16 v[122:125], v[10:13], v[6:9], v[150:153]
	v_addc_co_u32_e32 v35, vcc, 0, v163, vcc
	s_nop 1
	global_load_dwordx4 v[150:153], v[34:35], off offset:3072
	v_mfma_f32_16x16x32_bf16 v[126:129], v[14:17], v[6:9], v[130:133]
	s_waitcnt vmcnt(1)
	v_mfma_f32_16x16x32_bf16 v[118:121], v[198:201], v[6:9], v[154:157]
	s_nop 0
	v_lshl_or_b32 v130, v170, 2, v168
	s_waitcnt vmcnt(0)
	v_mfma_f32_16x16x32_bf16 v[114:117], v[150:153], v[6:9], v[146:149]
	ds_read_b128 v[6:9], v0 offset:34816
	s_nop 1
	ds_read_b128 v[146:149], v0 offset:47104
	s_waitcnt lgkmcnt(1)
	v_mfma_f32_16x16x32_bf16 v[110:113], v[14:17], v[6:9], v[158:161]
	v_mfma_f32_16x16x32_bf16 v[106:109], v[10:13], v[6:9], v[106:109]
	v_mfma_f32_16x16x32_bf16 v[102:105], v[198:201], v[6:9], v[102:105]
	v_mfma_f32_16x16x32_bf16 v[98:101], v[150:153], v[6:9], v[98:101]
	ds_read_b128 v[6:9], v0 offset:36864
	s_waitcnt lgkmcnt(0)
	v_mfma_f32_16x16x32_bf16 v[94:97], v[14:17], v[6:9], v[94:97]
	v_mfma_f32_16x16x32_bf16 v[90:93], v[10:13], v[6:9], v[86:89]
	v_mfma_f32_16x16x32_bf16 v[86:89], v[198:201], v[6:9], v[82:85]
	v_mfma_f32_16x16x32_bf16 v[82:85], v[150:153], v[6:9], v[78:81]
	ds_read_b128 v[6:9], v0 offset:38912
	s_waitcnt lgkmcnt(0)
	v_mfma_f32_16x16x32_bf16 v[78:81], v[14:17], v[6:9], v[74:77]
	v_mfma_f32_16x16x32_bf16 v[74:77], v[10:13], v[6:9], v[70:73]
	v_mfma_f32_16x16x32_bf16 v[70:73], v[198:201], v[6:9], v[62:65]
	v_mfma_f32_16x16x32_bf16 v[66:69], v[150:153], v[6:9], v[66:69]
	ds_read_b128 v[6:9], v0 offset:40960
	s_waitcnt lgkmcnt(0)
	v_mfma_f32_16x16x32_bf16 v[62:65], v[14:17], v[6:9], v[46:49]
	v_mfma_f32_16x16x32_bf16 v[58:61], v[10:13], v[6:9], v[50:53]
	v_mfma_f32_16x16x32_bf16 v[54:57], v[198:201], v[6:9], v[164:167]
	v_mfma_f32_16x16x32_bf16 v[50:53], v[150:153], v[6:9], v[172:175]
	ds_read_b128 v[6:9], v0 offset:43008
	s_waitcnt lgkmcnt(0)
	v_mfma_f32_16x16x32_bf16 v[46:49], v[14:17], v[6:9], v[26:29]
	v_mfma_f32_16x16x32_bf16 v[42:45], v[10:13], v[6:9], v[22:25]
	v_mfma_f32_16x16x32_bf16 v[38:41], v[198:201], v[6:9], v[18:21]
	v_mfma_f32_16x16x32_bf16 v[34:37], v[150:153], v[6:9], v[176:179]
	ds_read_b128 v[6:9], v0 offset:45056
	v_and_b32_e32 v0, 0xffffff80, v169
	v_add_u32_e32 v0, s0, v0
	v_and_or_b32 v132, v169, 15, v0
	v_ashrrev_i32_e32 v133, 31, v132
	s_waitcnt lgkmcnt(0)
	v_mfma_f32_16x16x32_bf16 v[30:33], v[14:17], v[6:9], v[30:33]
	s_movk_i32 s0, 0x4010
	v_cmp_gt_i32_e64 s[0:1], s0, v132
	v_mfma_f32_16x16x32_bf16 v[14:17], v[14:17], v[146:149], v[2:5]
	s_barrier
	s_nop 1
	v_lshlrev_b64 v[2:3], 6, v[132:133]
	v_mfma_f32_16x16x32_bf16 v[26:29], v[10:13], v[6:9], v[180:183]
	v_mfma_f32_16x16x32_bf16 v[10:13], v[10:13], v[146:149], v[134:137]
	s_nop 2
	v_lshl_add_u64 v[136:137], s[6:7], 0, v[2:3]
	v_mov_b64_e32 v[2:3], s[30:31]
	v_mfma_f32_16x16x32_bf16 v[22:25], v[198:201], v[6:9], v[190:193]
	v_mad_i64_i32 v[134:135], s[10:11], v132, s10, v[2:3]
	v_mfma_f32_16x16x32_bf16 v[18:21], v[150:153], v[6:9], v[142:145]
	v_mfma_f32_16x16x32_bf16 v[6:9], v[198:201], v[146:149], v[138:141]
	v_mfma_f32_16x16x32_bf16 v[2:5], v[150:153], v[146:149], v[194:197]
	s_and_saveexec_b64 s[10:11], s[0:1]
	s_cbranch_execz .LBB0_1375
	s_movk_i32 s13, 0xbff
	v_cmp_lt_i32_e32 vcc, s13, v130
	s_and_saveexec_b64 s[16:17], vcc
	s_xor_b64 s[16:17], exec, s[16:17]
	s_cbranch_execz .LBB0_1373
	s_movk_i32 s13, 0xc10
	v_cmp_gt_u32_e32 vcc, s13, v168
	s_and_saveexec_b64 s[34:35], vcc
	s_cbranch_execz .LBB0_1372
	v_mov_b32_e32 v131, v1
	v_lshl_add_u64 v[138:139], v[130:131], 2, v[136:137]
	v_add_co_u32_e32 v138, vcc, 0xffffd000, v138
	s_nop 1
	v_addc_co_u32_e32 v139, vcc, -1, v139, vcc
	global_store_dwordx4 v[138:139], v[126:129], off

; #define MFMA16(a, b, c) __builtin_amdgcn_mfma_f32_16x16x32_bf16((a), (b), (c), 0, 0, 0)
; template <class Epi>
; DEVI void gemm_tile256b(const bf16_t* __restrict__ A, int lda, const bf16_t* __restrict__ Bt, int K,
;                         int m0, int n0, char* smem, Epi epi) {
;     ...
;   for (int kt = 0; kt < nk; ++kt) {
;     const char* base = smem + (kt & 1) * 32768;
;     const bool more = kt + 1 < nk;
;     if (more) {
; #pragma unroll
;       for (int i = 0; i < 8; ++i) ra[i] = *(const u32x4*)(ag + (size_t)(i * 32) * lda + (kt + 1) * 64);
;     }
; #pragma unroll
;     for (int i = 0; i < 4; ++i) b1[i] = *(const bf16x8*)(bp + ((size_t)i * kb32 + kt * 2 + 1) * 512);
;     {
;       bf16x8 af[8];
; #pragma unroll
;       for (int i = 0; i < 8; ++i) af[i] = *(const bf16x8*)(base + a_rd + i * 2048);
; #pragma unroll
;       for (int mi = 0; mi < 8; ++mi)
; #pragma unroll
;         for (int ni = 0; ni < 4; ++ni) acc[mi][ni] = MFMA16(b0[ni], af[mi], acc[mi][ni]);
;     }
;     if (more) {
; #pragma unroll
;       for (int i = 0; i < 4; ++i) b0[i] = *(const bf16x8*)(bp + ((size_t)i * kb32 + kt * 2 + 2) * 512);
;     }
;     {
;       bf16x8 af[8];
; #pragma unroll
;       for (int i = 0; i < 8; ++i) af[i] = *(const bf16x8*)(base + ((a_rd + i * 2048) ^ 64));
; #pragma unroll
;       for (int mi = 0; mi < 8; ++mi)
; #pragma unroll
;         for (int ni = 0; ni < 4; ++ni) acc[mi][ni] = MFMA16(b1[ni], af[mi], acc[mi][ni]);
;     }
;     if (more) {
;       char* nb = smem + ((kt + 1) & 1) * 32768 + lds_w;
; #pragma unroll
;       for (int i = 0; i < 8; ++i) *(u32x4*)(nb + i * 4096) = ra[i];
;     }
;     __syncthreads();
;   }
.LBB0_1873:
	s_add_i32 s10, s1, 0xffff8000
	s_and_b32 s10, s10, 0x8000
	s_add_i32 s10, s10, 32
	v_add_u32_e32 v0, s10, v173
	ds_read_b128 v[146:149], v0
	ds_read_b128 v[150:153], v0 offset:2048
	v_lshl_add_u64 v[154:155], v[164:165], 0, s[28:29]
	s_mov_b32 s11, 0x2a80000
	v_add_co_u32_e32 v156, vcc, s11, v154
	s_waitcnt vmcnt(3) lgkmcnt(1)
	v_mfma_f32_16x16x32_bf16 v[134:137], v[10:13], v[146:149], v[134:137]
	v_addc_co_u32_e32 v157, vcc, 0, v155, vcc
	s_mov_b32 s11, 0x2a88000
	s_waitcnt vmcnt(2)
	v_mfma_f32_16x16x32_bf16 v[130:133], v[14:17], v[146:149], v[130:133]
	v_add_co_u32_e32 v158, vcc, s11, v154
	s_mov_b32 s11, 0x2a90000
	s_waitcnt vmcnt(1)
	v_mfma_f32_16x16x32_bf16 v[126:129], v[6:9], v[146:149], v[126:129]
	v_addc_co_u32_e32 v159, vcc, 0, v155, vcc
	v_add_co_u32_e32 v160, vcc, s11, v154
	s_waitcnt vmcnt(0)
	v_mfma_f32_16x16x32_bf16 v[122:125], v[2:5], v[146:149], v[122:125]
	v_addc_co_u32_e32 v161, vcc, 0, v155, vcc
	s_mov_b32 s11, 0x2a98000
	s_waitcnt lgkmcnt(0)
	v_mfma_f32_16x16x32_bf16 v[114:117], v[10:13], v[150:153], v[114:117]
	v_add_co_u32_e32 v182, vcc, s11, v154
	v_mfma_f32_16x16x32_bf16 v[110:113], v[14:17], v[150:153], v[110:113]
	v_addc_co_u32_e32 v183, vcc, 0, v155, vcc
	v_mfma_f32_16x16x32_bf16 v[106:109], v[6:9], v[150:153], v[106:109]
	s_nop 0
	v_mfma_f32_16x16x32_bf16 v[102:105], v[2:5], v[150:153], v[102:105]
	ds_read_b128 v[146:149], v0 offset:4096
	ds_read_b128 v[150:153], v0 offset:6144
	s_waitcnt lgkmcnt(1)
	v_mfma_f32_16x16x32_bf16 v[98:101], v[10:13], v[146:149], v[98:101]
	v_lshl_add_u64 v[164:165], v[164:165], 0, s[64:65]
	v_mfma_f32_16x16x32_bf16 v[94:97], v[14:17], v[146:149], v[94:97]
	v_mfma_f32_16x16x32_bf16 v[86:89], v[6:9], v[146:149], v[86:89]
	s_nop 0
	v_mfma_f32_16x16x32_bf16 v[82:85], v[2:5], v[146:149], v[82:85]
	s_nop 0
	s_waitcnt lgkmcnt(0)
	v_mfma_f32_16x16x32_bf16 v[74:77], v[10:13], v[150:153], v[74:77]
	v_mfma_f32_16x16x32_bf16 v[70:73], v[14:17], v[150:153], v[70:73]
	s_nop 0
	v_lshl_add_u64 v[166:167], v[166:167], 0, s[60:61]
	v_mfma_f32_16x16x32_bf16 v[62:65], v[6:9], v[150:153], v[62:65]
	v_mfma_f32_16x16x32_bf16 v[66:69], v[2:5], v[150:153], v[66:69]
	ds_read_b128 v[146:149], v0 offset:8192
	ds_read_b128 v[150:153], v0 offset:10240
	s_waitcnt lgkmcnt(1)
	v_mfma_f32_16x16x32_bf16 v[46:49], v[10:13], v[146:149], v[46:49]
	v_mfma_f32_16x16x32_bf16 v[50:53], v[14:17], v[146:149], v[50:53]
	v_mfma_f32_16x16x32_bf16 v[58:61], v[6:9], v[146:149], v[58:61]
	v_mfma_f32_16x16x32_bf16 v[54:57], v[2:5], v[146:149], v[54:57]
	s_waitcnt lgkmcnt(0)
	v_mfma_f32_16x16x32_bf16 v[26:29], v[10:13], v[150:153], v[26:29]
	v_mfma_f32_16x16x32_bf16 v[22:25], v[14:17], v[150:153], v[22:25]
	v_mfma_f32_16x16x32_bf16 v[18:21], v[6:9], v[150:153], v[18:21]
	v_mfma_f32_16x16x32_bf16 v[42:45], v[2:5], v[150:153], v[42:45]
	ds_read_b128 v[146:149], v0 offset:12288
	ds_read_b128 v[150:153], v0 offset:14336
	v_add_u32_e32 v0, s10, v171
	s_and_b32 s10, s1, 0x8000
	s_waitcnt lgkmcnt(1)
	v_mfma_f32_16x16x32_bf16 v[34:37], v[10:13], v[146:149], v[34:37]
	s_add_i32 s1, s1, 0x8000
	s_cmp_eq_u32 s1, 0x80000
	v_mfma_f32_16x16x32_bf16 v[38:41], v[14:17], v[146:149], v[38:41]
	v_mfma_f32_16x16x32_bf16 v[30:33], v[6:9], v[146:149], v[30:33]
	v_mfma_f32_16x16x32_bf16 v[142:145], v[2:5], v[146:149], v[142:145]
	global_load_dwordx4 v[146:149], v[156:157], off offset:1024
	ds_read_b128 v[174:177], v0
	ds_read_b128 v[178:181], v0 offset:2048
	s_waitcnt lgkmcnt(2)
	v_mfma_f32_16x16x32_bf16 v[138:141], v[10:13], v[150:153], v[138:141]
	global_load_dwordx4 v[10:13], v[156:157], off offset:2048
	v_mfma_f32_16x16x32_bf16 v[118:121], v[14:17], v[150:153], v[118:121]
	v_mfma_f32_16x16x32_bf16 v[90:93], v[6:9], v[150:153], v[90:93]
	v_mfma_f32_16x16x32_bf16 v[78:81], v[2:5], v[150:153], v[78:81]
	global_load_dwordx4 v[150:153], v[158:159], off offset:1024
	global_load_dwordx4 v[14:17], v[158:159], off offset:2048
	global_load_dwordx4 v[154:157], v[160:161], off offset:1024
	global_load_dwordx4 v[6:9], v[160:161], off offset:2048
	s_nop 0
	global_load_dwordx4 v[158:161], v[182:183], off offset:1024
	global_load_dwordx4 v[2:5], v[182:183], off offset:2048
	v_lshrrev_b32_e32 v195, 6, v206
	v_lshl_add_u64 v[190:191], v[166:167], 0, s[28:29]
	v_lshrrev_b32_e32 v194, 3, v206
	v_readfirstlane_b32 s99, v195
	v_and_b32_e32 v194, 7, v194
	s_and_b32 s98, s1, 0x8000
	s_xor_b32 s98, s98, 0x8000
	v_lshlrev_b32_e32 v194, 4, v194
	s_lshl_b32 s99, s99, 10
	v_xor_b32_e32 v190, v194, v190
	s_add_u32 s98, s98, s99
	s_add_u32 s98, s98, 32
	s_mov_b32 s101, 0
	s_mov_b32 s100, 0x0
	v_lshl_add_u64 v[192:193], v[190:191], 0, s[100:101]
	s_mov_b32 m0, s98
	s_nop 0
	global_load_lds_dwordx4 v[192:193], off
	s_add_u32 s100, s54, 0x0
	v_lshl_add_u64 v[192:193], v[190:191], 0, s[100:101]
	s_add_u32 m0, s98, 0x1000
	s_nop 0
	global_load_lds_dwordx4 v[192:193], off
	s_add_u32 s100, s53, 0x0
	v_lshl_add_u64 v[192:193], v[190:191], 0, s[100:101]
	s_add_u32 m0, s98, 0x2000
	s_nop 0
	global_load_lds_dwordx4 v[192:193], off
	s_add_u32 s100, s52, 0x0
	v_lshl_add_u64 v[192:193], v[190:191], 0, s[100:101]
	s_add_u32 m0, s98, 0x3000
	s_nop 0
	global_load_lds_dwordx4 v[192:193], off
	s_add_u32 s100, s56, 0x0
	v_lshl_add_u64 v[192:193], v[190:191], 0, s[100:101]
	s_add_u32 m0, s98, 0x4000
	s_nop 0
	global_load_lds_dwordx4 v[192:193], off
	s_add_u32 s100, s57, 0x0
	v_lshl_add_u64 v[192:193], v[190:191], 0, s[100:101]
	s_add_u32 m0, s98, 0x5000
	s_nop 0
	global_load_lds_dwordx4 v[192:193], off
	s_add_u32 s100, s3, 0x0
	v_lshl_add_u64 v[192:193], v[190:191], 0, s[100:101]
	s_add_u32 m0, s98, 0x6000
	s_nop 0
	global_load_lds_dwordx4 v[192:193], off
	s_add_u32 s100, s19, 0x0
	v_lshl_add_u64 v[192:193], v[190:191], 0, s[100:101]
	s_add_u32 m0, s98, 0x7000
	s_nop 0
	global_load_lds_dwordx4 v[192:193], off
	s_waitcnt vmcnt(15) lgkmcnt(1)
; #define MFMA16(a, b, c) __builtin_amdgcn_mfma_f32_16x16x32_bf16((a), (b), (c), 0, 0, 0)
; template <class Epi>
; DEVI void gemm_tile256b(const bf16_t* __restrict__ A, int lda, const bf16_t* __restrict__ Bt, int K,
;                         int m0, int n0, char* smem, Epi epi) {
;     ...
;   for (int kt = 0; kt < nk; ++kt) {
;     const char* base = smem + (kt & 1) * 32768;
;     const bool more = kt + 1 < nk;
;     if (more) {
; #pragma unroll
;       for (int i = 0; i < 8; ++i) ra[i] = *(const u32x4*)(ag + (size_t)(i * 32) * lda + (kt + 1) * 64);
;     }
; #pragma unroll
;     for (int i = 0; i < 4; ++i) b1[i] = *(const bf16x8*)(bp + ((size_t)i * kb32 + kt * 2 + 1) * 512);
;     {
;       bf16x8 af[8];
; #pragma unroll
;       for (int i = 0; i < 8; ++i) af[i] = *(const bf16x8*)(base + a_rd + i * 2048);
; #pragma unroll
;       for (int mi = 0; mi < 8; ++mi)
; #pragma unroll
;         for (int ni = 0; ni < 4; ++ni) acc[mi][ni] = MFMA16(b0[ni], af[mi], acc[mi][ni]);
;     }
;     if (more) {
; #pragma unroll
;       for (int i = 0; i < 4; ++i) b0[i] = *(const bf16x8*)(bp + ((size_t)i * kb32 + kt * 2 + 2) * 512);
;     }
;     {
;       bf16x8 af[8];
; #pragma unroll
;       for (int i = 0; i < 8; ++i) af[i] = *(const bf16x8*)(base + ((a_rd + i * 2048) ^ 64));
; #pragma unroll
;       for (int mi = 0; mi < 8; ++mi)
; #pragma unroll
;         for (int ni = 0; ni < 4; ++ni) acc[mi][ni] = MFMA16(b1[ni], af[mi], acc[mi][ni]);
;     }
;     if (more) {
;       char* nb = smem + ((kt + 1) & 1) * 32768 + lds_w;
; #pragma unroll
;       for (int i = 0; i < 8; ++i) *(u32x4*)(nb + i * 4096) = ra[i];
;     }
;     __syncthreads();
;   }
	v_mfma_f32_16x16x32_bf16 v[134:137], v[146:149], v[174:177], v[134:137]
	s_waitcnt vmcnt(13)
	v_mfma_f32_16x16x32_bf16 v[130:133], v[150:153], v[174:177], v[130:133]
	s_waitcnt vmcnt(11)
	v_mfma_f32_16x16x32_bf16 v[126:129], v[154:157], v[174:177], v[126:129]
	s_waitcnt vmcnt(9)
	v_mfma_f32_16x16x32_bf16 v[122:125], v[158:161], v[174:177], v[122:125]
	s_waitcnt lgkmcnt(0)
	v_mfma_f32_16x16x32_bf16 v[114:117], v[146:149], v[178:181], v[114:117]
	v_mfma_f32_16x16x32_bf16 v[110:113], v[150:153], v[178:181], v[110:113]
	v_mfma_f32_16x16x32_bf16 v[106:109], v[154:157], v[178:181], v[106:109]
	v_mfma_f32_16x16x32_bf16 v[102:105], v[158:161], v[178:181], v[102:105]
	ds_read_b128 v[174:177], v0 offset:4096
	ds_read_b128 v[178:181], v0 offset:6144
	s_waitcnt lgkmcnt(1)
	v_mfma_f32_16x16x32_bf16 v[98:101], v[146:149], v[174:177], v[98:101]
	v_mfma_f32_16x16x32_bf16 v[94:97], v[150:153], v[174:177], v[94:97]
	v_mfma_f32_16x16x32_bf16 v[86:89], v[154:157], v[174:177], v[86:89]
	v_mfma_f32_16x16x32_bf16 v[82:85], v[158:161], v[174:177], v[82:85]
	s_waitcnt lgkmcnt(0)
	v_mfma_f32_16x16x32_bf16 v[74:77], v[146:149], v[178:181], v[74:77]
	v_mfma_f32_16x16x32_bf16 v[70:73], v[150:153], v[178:181], v[70:73]
	v_mfma_f32_16x16x32_bf16 v[62:65], v[154:157], v[178:181], v[62:65]
	v_mfma_f32_16x16x32_bf16 v[66:69], v[158:161], v[178:181], v[66:69]
	ds_read_b128 v[178:181], v0 offset:8192
	ds_read_b128 v[182:185], v0 offset:10240
	s_waitcnt lgkmcnt(1)
	v_mfma_f32_16x16x32_bf16 v[46:49], v[146:149], v[178:181], v[46:49]
	v_mfma_f32_16x16x32_bf16 v[50:53], v[150:153], v[178:181], v[50:53]
	v_mfma_f32_16x16x32_bf16 v[58:61], v[154:157], v[178:181], v[58:61]
	v_mfma_f32_16x16x32_bf16 v[54:57], v[158:161], v[178:181], v[54:57]
	s_waitcnt lgkmcnt(0)
	v_mfma_f32_16x16x32_bf16 v[26:29], v[146:149], v[182:185], v[26:29]
	v_mfma_f32_16x16x32_bf16 v[22:25], v[150:153], v[182:185], v[22:25]
	v_mfma_f32_16x16x32_bf16 v[18:21], v[154:157], v[182:185], v[18:21]
	v_mfma_f32_16x16x32_bf16 v[42:45], v[158:161], v[182:185], v[42:45]
	ds_read_b128 v[178:181], v0 offset:12288
	ds_read_b128 v[182:185], v0 offset:14336
	s_nop 0
	s_nop 0
	s_nop 0
	s_nop 0
	s_nop 0
	s_waitcnt lgkmcnt(1)
	v_mfma_f32_16x16x32_bf16 v[34:37], v[146:149], v[178:181], v[34:37]
	v_mfma_f32_16x16x32_bf16 v[38:41], v[150:153], v[178:181], v[38:41]
	v_mfma_f32_16x16x32_bf16 v[30:33], v[154:157], v[178:181], v[30:33]
	s_waitcnt vmcnt(0) lgkmcnt(0)
	s_barrier
	v_mfma_f32_16x16x32_bf16 v[142:145], v[158:161], v[178:181], v[142:145]
	v_mfma_f32_16x16x32_bf16 v[138:141], v[146:149], v[182:185], v[138:141]
	v_mfma_f32_16x16x32_bf16 v[118:121], v[150:153], v[182:185], v[118:121]
	v_mfma_f32_16x16x32_bf16 v[90:93], v[154:157], v[182:185], v[90:93]
	v_mfma_f32_16x16x32_bf16 v[78:81], v[158:161], v[182:185], v[78:81]
	s_cmp_eq_u32 s1, 0x80000
	s_cbranch_scc0 .LBB0_1873
	v_add_u32_e32 v0, 32, v173
	ds_read_b128 v[146:149], v0 offset:32768
	s_movk_i32 s1, 0x7000
	s_waitcnt lgkmcnt(0)
	v_mfma_f32_16x16x32_bf16 v[134:137], v[10:13], v[146:149], v[134:137]
	v_mfma_f32_16x16x32_bf16 v[130:133], v[14:17], v[146:149], v[130:133]
	v_mfma_f32_16x16x32_bf16 v[150:153], v[6:9], v[146:149], v[126:129]
	v_mfma_f32_16x16x32_bf16 v[146:149], v[2:5], v[146:149], v[122:125]
	s_nop 2
	ds_read_b128 v[122:125], v0 offset:34816
	s_waitcnt lgkmcnt(0)
	v_mfma_f32_16x16x32_bf16 v[164:167], v[2:5], v[122:125], v[102:105]
	s_nop 2
	ds_read_b128 v[102:105], v0 offset:36864
	s_waitcnt lgkmcnt(0)
	v_mfma_f32_16x16x32_bf16 v[176:179], v[14:17], v[102:105], v[94:97]
	s_nop 2
	ds_read_b128 v[94:97], v0 offset:38912
	s_waitcnt lgkmcnt(0)
	v_mfma_f32_16x16x32_bf16 v[74:77], v[10:13], v[94:97], v[74:77]
	v_mfma_f32_16x16x32_bf16 v[70:73], v[14:17], v[94:97], v[70:73]
	v_mfma_f32_16x16x32_bf16 v[62:65], v[6:9], v[94:97], v[62:65]
	v_mfma_f32_16x16x32_bf16 v[66:69], v[2:5], v[94:97], v[66:69]
	ds_read_b128 v[94:97], v0 offset:40960
	s_waitcnt lgkmcnt(0)
	v_mfma_f32_16x16x32_bf16 v[190:193], v[2:5], v[94:97], v[54:57]
	s_nop 2
	ds_read_b128 v[54:57], v0 offset:43008
	s_waitcnt lgkmcnt(0)
	v_mfma_f32_16x16x32_bf16 v[194:197], v[2:5], v[54:57], v[42:45]
	s_nop 2
	ds_read_b128 v[42:45], v0 offset:45056
	s_waitcnt lgkmcnt(0)
	v_mfma_f32_16x16x32_bf16 v[226:229], v[6:9], v[42:45], v[30:33]
	s_nop 2
	ds_read_b128 v[30:33], v0 offset:47104
	v_add_u32_e32 v0, 32, v171
	v_mfma_f32_16x16x32_bf16 v[114:117], v[10:13], v[122:125], v[114:117]
	v_mfma_f32_16x16x32_bf16 v[154:157], v[14:17], v[122:125], v[110:113]
	v_mfma_f32_16x16x32_bf16 v[172:175], v[10:13], v[102:105], v[98:101]
	v_mfma_f32_16x16x32_bf16 v[46:49], v[10:13], v[94:97], v[46:49]
	v_mfma_f32_16x16x32_bf16 v[50:53], v[14:17], v[94:97], v[50:53]
	v_mfma_f32_16x16x32_bf16 v[26:29], v[10:13], v[54:57], v[26:29]
	v_mfma_f32_16x16x32_bf16 v[22:25], v[14:17], v[54:57], v[22:25]
	v_mfma_f32_16x16x32_bf16 v[198:201], v[10:13], v[42:45], v[34:37]
	v_mfma_f32_16x16x32_bf16 v[202:205], v[14:17], v[42:45], v[38:41]
	s_waitcnt lgkmcnt(0)
	v_mfma_f32_16x16x32_bf16 v[10:13], v[10:13], v[30:33], v[138:141]
	v_mfma_f32_16x16x32_bf16 v[138:141], v[14:17], v[30:33], v[118:121]
	v_add_co_u32_e32 v14, vcc, s1, v162
	s_mov_b32 s1, 0xf000
	s_nop 0
	v_addc_co_u32_e32 v15, vcc, 0, v163, vcc
	global_load_dwordx4 v[14:17], v[14:15], off offset:3072
	v_mfma_f32_16x16x32_bf16 v[158:161], v[6:9], v[122:125], v[106:109]
	v_add_co_u32_e32 v34, vcc, s1, v162
	s_mov_b32 s1, 0x17000
	v_mfma_f32_16x16x32_bf16 v[86:89], v[6:9], v[102:105], v[86:89]
	v_addc_co_u32_e32 v35, vcc, 0, v163, vcc
	global_load_dwordx4 v[230:233], v[34:35], off offset:3072
	v_mfma_f32_16x16x32_bf16 v[82:85], v[2:5], v[102:105], v[82:85]
	v_add_co_u32_e32 v34, vcc, s1, v162
	s_mov_b32 s1, 0x1f000
	v_mfma_f32_16x16x32_bf16 v[180:183], v[6:9], v[94:97], v[58:61]
	v_addc_co_u32_e32 v35, vcc, 0, v163, vcc
	v_mfma_f32_16x16x32_bf16 v[18:21], v[6:9], v[54:57], v[18:21]
	v_mfma_f32_16x16x32_bf16 v[142:145], v[2:5], v[42:45], v[142:145]
	v_mfma_f32_16x16x32_bf16 v[6:9], v[6:9], v[30:33], v[90:93]
	v_mfma_f32_16x16x32_bf16 v[2:5], v[2:5], v[30:33], v[78:81]
	ds_read_b128 v[30:33], v0 offset:32768
	s_waitcnt vmcnt(1) lgkmcnt(0)
; #define MFMA16(a, b, c) __builtin_amdgcn_mfma_f32_16x16x32_bf16((a), (b), (c), 0, 0, 0)
; template <class Epi>
; DEVI void gemm_tile256b(const bf16_t* __restrict__ A, int lda, const bf16_t* __restrict__ Bt, int K,
;                         int m0, int n0, char* smem, Epi epi) {
;     ...
;     for (int i = 0; i < 4; ++i) b1[i] = *(const bf16x8*)(bp + ((size_t)i * kb32 + kt * 2 + 1) * 512);
;     {
;       bf16x8 af[8];
; #pragma unroll
;       for (int i = 0; i < 8; ++i) af[i] = *(const bf16x8*)(base + a_rd + i * 2048);
; #pragma unroll
;       for (int mi = 0; mi < 8; ++mi)
; #pragma unroll
;         for (int ni = 0; ni < 4; ++ni) acc[mi][ni] = MFMA16(b0[ni], af[mi], acc[mi][ni]);
;     }
;     if (more) {
; #pragma unroll
;       for (int i = 0; i < 4; ++i) b0[i] = *(const bf16x8*)(bp + ((size_t)i * kb32 + kt * 2 + 2) * 512);
;     }
;     {
;       bf16x8 af[8];
; #pragma unroll
;       for (int i = 0; i < 8; ++i) af[i] = *(const bf16x8*)(base + ((a_rd + i * 2048) ^ 64));
; #pragma unroll
;       for (int mi = 0; mi < 8; ++mi)
; #pragma unroll
;         for (int ni = 0; ni < 4; ++ni) acc[mi][ni] = MFMA16(b1[ni], af[mi], acc[mi][ni]);
;     }
;     if (more) {
;       char* nb = smem + ((kt + 1) & 1) * 32768 + lds_w;
; #pragma unroll
;       for (int i = 0; i < 8; ++i) *(u32x4*)(nb + i * 4096) = ra[i];
;     }
;     __syncthreads();
;   }
; #pragma unroll
;   for (int mi = 0; mi < 8; ++mi)
; #pragma unroll
;     for (int ni = 0; ni < 4; ++ni)
;       epi(m0 + wm * 128 + mi * 16 + l15, n0 + wn * 64 + ni * 16 + quad * 4, acc[mi][ni]);
;   DEVI void operator()(int m, int n, f32x4 v) const {
;     if (m >= L) return;
;     float a = fmaxf(v[0], 0.f), b = fmaxf(v[1], 0.f), c = fmaxf(v[2], 0.f), d = fmaxf(v[3], 0.f);
;     *(u32x2*)(hid + (size_t)m * 4096 + n) = u32x2{pack2(a * a, b * b), pack2(c * c, d * d)};
	v_mfma_f32_16x16x32_bf16 v[126:129], v[14:17], v[30:33], v[134:137]
	s_nop 2
	global_load_dwordx4 v[134:137], v[34:35], off offset:3072
	v_add_co_u32_e32 v34, vcc, s1, v162
	s_waitcnt vmcnt(1)
	v_mfma_f32_16x16x32_bf16 v[122:125], v[230:233], v[30:33], v[130:133]
	v_addc_co_u32_e32 v35, vcc, 0, v163, vcc
	s_nop 1
	v_lshl_or_b32 v130, v169, 2, v170
	s_waitcnt vmcnt(0)
	v_mfma_f32_16x16x32_bf16 v[118:121], v[134:137], v[30:33], v[150:153]
	s_nop 2
	global_load_dwordx4 v[150:153], v[34:35], off offset:3072
	v_ashrrev_i32_e32 v131, 31, v130
	s_waitcnt vmcnt(0)
	v_mfma_f32_16x16x32_bf16 v[110:113], v[150:153], v[30:33], v[146:149]
	ds_read_b128 v[30:33], v0 offset:34816
	s_waitcnt lgkmcnt(0)
	v_mfma_f32_16x16x32_bf16 v[114:117], v[14:17], v[30:33], v[114:117]
	v_mfma_f32_16x16x32_bf16 v[106:109], v[230:233], v[30:33], v[154:157]
	v_mfma_f32_16x16x32_bf16 v[102:105], v[134:137], v[30:33], v[158:161]
	v_mfma_f32_16x16x32_bf16 v[98:101], v[150:153], v[30:33], v[164:167]
	ds_read_b128 v[30:33], v0 offset:36864
	s_waitcnt lgkmcnt(0)
	v_mfma_f32_16x16x32_bf16 v[94:97], v[14:17], v[30:33], v[172:175]
	v_mfma_f32_16x16x32_bf16 v[90:93], v[230:233], v[30:33], v[176:179]
	v_mfma_f32_16x16x32_bf16 v[86:89], v[134:137], v[30:33], v[86:89]
	v_mfma_f32_16x16x32_bf16 v[82:85], v[150:153], v[30:33], v[82:85]
	ds_read_b128 v[30:33], v0 offset:38912
	s_waitcnt lgkmcnt(0)
	v_mfma_f32_16x16x32_bf16 v[78:81], v[14:17], v[30:33], v[74:77]
	v_mfma_f32_16x16x32_bf16 v[74:77], v[230:233], v[30:33], v[70:73]
	v_mfma_f32_16x16x32_bf16 v[70:73], v[134:137], v[30:33], v[62:65]
	v_mfma_f32_16x16x32_bf16 v[66:69], v[150:153], v[30:33], v[66:69]
	ds_read_b128 v[30:33], v0 offset:40960
	s_waitcnt lgkmcnt(0)
	v_mfma_f32_16x16x32_bf16 v[62:65], v[14:17], v[30:33], v[46:49]
	v_mfma_f32_16x16x32_bf16 v[58:61], v[230:233], v[30:33], v[50:53]
	v_mfma_f32_16x16x32_bf16 v[54:57], v[134:137], v[30:33], v[180:183]
	v_mfma_f32_16x16x32_bf16 v[50:53], v[150:153], v[30:33], v[190:193]
	ds_read_b128 v[30:33], v0 offset:43008
	s_waitcnt lgkmcnt(0)
	v_mfma_f32_16x16x32_bf16 v[38:41], v[134:137], v[30:33], v[18:21]
	s_nop 2
	ds_read_b128 v[18:21], v0 offset:45056
	v_mfma_f32_16x16x32_bf16 v[46:49], v[14:17], v[30:33], v[26:29]
	v_mfma_f32_16x16x32_bf16 v[42:45], v[230:233], v[30:33], v[22:25]
	v_mfma_f32_16x16x32_bf16 v[34:37], v[150:153], v[30:33], v[194:197]
	s_waitcnt lgkmcnt(0)
	v_mfma_f32_16x16x32_bf16 v[30:33], v[14:17], v[18:21], v[198:201]
	v_mfma_f32_16x16x32_bf16 v[26:29], v[230:233], v[18:21], v[202:205]
	v_mfma_f32_16x16x32_bf16 v[22:25], v[134:137], v[18:21], v[226:229]
	v_mfma_f32_16x16x32_bf16 v[18:21], v[150:153], v[18:21], v[142:145]
	s_nop 2
	ds_read_b128 v[142:145], v0 offset:47104
	s_waitcnt lgkmcnt(0)
	v_mfma_f32_16x16x32_bf16 v[14:17], v[14:17], v[142:145], v[10:13]
	v_and_b32_e32 v0, 0xffffff80, v168
	v_add_u32_e32 v0, s0, v0
	v_and_or_b32 v132, v168, 15, v0
	v_mfma_f32_16x16x32_bf16 v[10:13], v[230:233], v[142:145], v[138:141]
	s_movk_i32 s0, 0x4010
	v_cmp_gt_i32_e32 vcc, s0, v132
	v_mfma_f32_16x16x32_bf16 v[6:9], v[134:137], v[142:145], v[6:9]
	s_barrier
	v_mfma_f32_16x16x32_bf16 v[2:5], v[150:153], v[142:145], v[2:5]
	s_and_saveexec_b64 s[0:1], vcc
	s_cbranch_execz .LBB0_1876
	v_max_f32_e32 v0, v126, v126
	v_max_f32_e32 v126, 0, v0
	v_max_f32_e32 v0, v127, v127
	v_max_f32_e32 v127, 0, v0
	v_max_f32_e32 v0, v128, v128
	v_max_f32_e32 v128, 0, v0
	v_max_f32_e32 v0, v129, v129
	v_max_f32_e32 v129, 0, v0
	v_max_f32_e32 v0, v122, v122
	v_max_f32_e32 v122, 0, v0
	v_max_f32_e32 v0, v123, v123
	v_max_f32_e32 v123, 0, v0
	v_max_f32_e32 v0, v124, v124
	v_max_f32_e32 v124, 0, v0
	v_max_f32_e32 v0, v125, v125
	v_max_f32_e32 v125, 0, v0
	v_max_f32_e32 v0, v118, v118
	v_max_f32_e32 v118, 0, v0
	v_max_f32_e32 v0, v119, v119
	v_max_f32_e32 v119, 0, v0
	v_max_f32_e32 v0, v120, v120
	v_max_f32_e32 v120, 0, v0
	v_max_f32_e32 v0, v121, v121
	v_max_f32_e32 v121, 0, v0
	v_max_f32_e32 v0, v110, v110
	v_max_f32_e32 v110, 0, v0
	v_max_f32_e32 v0, v111, v111
	v_max_f32_e32 v111, 0, v0
	v_max_f32_e32 v0, v112, v112
	v_ashrrev_i32_e32 v133, 31, v132
	v_max_f32_e32 v112, 0, v0
	v_max_f32_e32 v0, v113, v113
	v_lshlrev_b64 v[134:135], 13, v[132:133]
	v_max_f32_e32 v113, 0, v0
	v_lshl_add_u64 v[134:135], s[30:31], 0, v[134:135]
	v_pk_mul_f32 v[126:127], v[126:127], v[126:127]
	v_pk_mul_f32 v[128:129], v[128:129], v[128:129]
	v_pk_mul_f32 v[122:123], v[122:123], v[122:123]
	v_pk_mul_f32 v[124:125], v[124:125], v[124:125]
	v_pk_mul_f32 v[118:119], v[118:119], v[118:119]
	v_pk_mul_f32 v[120:121], v[120:121], v[120:121]
	v_pk_mul_f32 v[110:111], v[110:111], v[110:111]
	v_pk_mul_f32 v[112:113], v[112:113], v[112:113]
	v_cvt_pk_bf16_f32 v126, v126, v127
	v_cvt_pk_bf16_f32 v127, v128, v129
	v_lshl_add_u64 v[128:129], v[130:131], 1, v[134:135]
	v_cvt_pk_bf16_f32 v122, v122, v123
	v_cvt_pk_bf16_f32 v123, v124, v125
	v_cvt_pk_bf16_f32 v118, v118, v119
	v_cvt_pk_bf16_f32 v119, v120, v121
	v_cvt_pk_bf16_f32 v110, v110, v111
	v_cvt_pk_bf16_f32 v111, v112, v113
	global_store_dwordx2 v[128:129], v[126:127], off
	global_store_dwordx2 v[128:129], v[122:123], off offset:32
	global_store_dwordx2 v[128:129], v[118:119], off offset:64
	global_store_dwordx2 v[128:129], v[110:111], off offset:96
